# hot loop headers (24 GEMM K-loops, 2 MoBA tile loops) aligned to 64 bytes
# baseline (speedup 1.0000x reference)
;     __device__ __forceinline__ bool next(int i, pg8::Unit& u) const { if (c < 128 || i >= 2) return false; const int idx = (c - 128) * 2 + i; u.pm = idx >> 2; u.pn = idx & 3; return true; }
; template <class Epi, class Sched, bool ALIGN_EPI = false, bool SP2 = false, bool F16 = false>
; __device__ __forceinline__ void gemm_phase(PG8_LAS unsigned char* lds, const Gemm g, const Sched& S, const Epi& E, const int wid_in) {
;     ...
;         const bool has_next = S.next(ui + 1, nxt);
;         const char* nA = has_next ? (const char*)g.A + (size_t)nxt.pm * tstep : cA; const char* nB = has_next ? (const char*)g.Bt + (size_t)nxt.pn * tstep : cB;
;     ...
; #pragma unroll
;         for (int a = 0; a < 2; ++a)
; #pragma unroll
;             for (int b = 0; b < 2; ++b)
; #pragma unroll
;                 for (int m = 0; m < 4; ++m)
; #pragma unroll
;                     for (int n = 0; n < 2; ++n) acc[a][b][m][n] = (f32x4){0.f, 0.f, 0.f, 0.f};
;         cur = nxt; cA = nA; cB = nB; ++ui;
.LBB0_223:
	s_ashr_i32 s51, s50, 31
	s_lshl_b64 s[42:43], s[50:51], 19
	s_add_u32 s52, s79, s42
	s_addc_u32 s53, s80, s43
	s_and_b64 s[42:43], s[6:7], exec
	s_cselect_b32 s9, s53, s57
	s_cselect_b32 s21, s52, s56
	s_ashr_i32 s49, s48, 31
	s_lshl_b64 s[42:43], s[48:49], 19
	s_add_u32 s54, s81, s42
	s_addc_u32 s55, s82, s43
	s_and_b64 s[42:43], s[6:7], exec
	s_cselect_b32 s42, s55, s59
	s_cselect_b32 s43, s54, s58
	s_add_u32 s56, s56, 0x40080
	s_addc_u32 s57, s57, 0
	s_add_u32 s49, s58, 0x100
	v_mov_b32_e32 v0, 0
	s_addc_u32 s51, s59, 0
	s_mov_b32 s62, -2
	s_waitcnt lgkmcnt(0)
	v_mov_b32_e32 v1, v0
	v_mov_b32_e32 v2, v0
	v_mov_b32_e32 v3, v0
	v_mov_b32_e32 v4, v0
	v_mov_b32_e32 v5, v0
	v_mov_b32_e32 v6, v0
	v_mov_b32_e32 v7, v0
	v_mov_b32_e32 v16, v0
	v_mov_b32_e32 v17, v0
	v_mov_b32_e32 v18, v0
	v_mov_b32_e32 v19, v0
	v_mov_b32_e32 v20, v0
	v_mov_b32_e32 v21, v0
	v_mov_b32_e32 v22, v0
	v_mov_b32_e32 v23, v0
	v_mov_b32_e32 v32, v0
	v_mov_b32_e32 v33, v0
	v_mov_b32_e32 v34, v0
	v_mov_b32_e32 v35, v0
	v_mov_b32_e32 v36, v0
	v_mov_b32_e32 v37, v0
	v_mov_b32_e32 v38, v0
	v_mov_b32_e32 v39, v0
	v_mov_b32_e32 v48, v0
	v_mov_b32_e32 v49, v0
	v_mov_b32_e32 v50, v0
	v_mov_b32_e32 v51, v0
	v_mov_b32_e32 v52, v0
	v_mov_b32_e32 v53, v0
	v_mov_b32_e32 v54, v0
	v_mov_b32_e32 v55, v0
	v_mov_b32_e32 v8, v0
	v_mov_b32_e32 v9, v0
	v_mov_b32_e32 v10, v0
	v_mov_b32_e32 v11, v0
	v_mov_b32_e32 v12, v0
	v_mov_b32_e32 v13, v0
	v_mov_b32_e32 v14, v0
	v_mov_b32_e32 v15, v0
	v_mov_b32_e32 v24, v0
	v_mov_b32_e32 v25, v0
	v_mov_b32_e32 v26, v0
	v_mov_b32_e32 v27, v0
	v_mov_b32_e32 v28, v0
	v_mov_b32_e32 v29, v0
	v_mov_b32_e32 v30, v0
	v_mov_b32_e32 v31, v0
	v_mov_b32_e32 v40, v0
	v_mov_b32_e32 v41, v0
	v_mov_b32_e32 v42, v0
	v_mov_b32_e32 v43, v0
	v_mov_b32_e32 v44, v0
	v_mov_b32_e32 v45, v0
	v_mov_b32_e32 v46, v0
	v_mov_b32_e32 v47, v0
	v_mov_b32_e32 v56, v0
	v_mov_b32_e32 v57, v0
	v_mov_b32_e32 v58, v0
	v_mov_b32_e32 v59, v0
	v_mov_b32_e32 v60, v0
	v_mov_b32_e32 v61, v0
	v_mov_b32_e32 v62, v0
	v_mov_b32_e32 v63, v0
	v_mov_b32_e32 v64, v0
	v_mov_b32_e32 v65, v0
	v_mov_b32_e32 v66, v0
	v_mov_b32_e32 v67, v0
	v_mov_b32_e32 v68, v0
	v_mov_b32_e32 v69, v0
	v_mov_b32_e32 v70, v0
	v_mov_b32_e32 v71, v0
	v_mov_b32_e32 v80, v0
	v_mov_b32_e32 v81, v0
	v_mov_b32_e32 v82, v0
	v_mov_b32_e32 v83, v0
	v_mov_b32_e32 v84, v0
	v_mov_b32_e32 v85, v0
	v_mov_b32_e32 v86, v0
	v_mov_b32_e32 v87, v0
	v_mov_b32_e32 v96, v0
	v_mov_b32_e32 v97, v0
	v_mov_b32_e32 v98, v0
	v_mov_b32_e32 v99, v0
	v_mov_b32_e32 v100, v0
	v_mov_b32_e32 v101, v0
	v_mov_b32_e32 v102, v0
	v_mov_b32_e32 v103, v0
	v_mov_b32_e32 v112, v0
	v_mov_b32_e32 v113, v0
	v_mov_b32_e32 v114, v0
	v_mov_b32_e32 v115, v0
	v_mov_b32_e32 v116, v0
	v_mov_b32_e32 v117, v0
	v_mov_b32_e32 v118, v0
	v_mov_b32_e32 v119, v0
	v_mov_b32_e32 v72, v0
	v_mov_b32_e32 v73, v0
	v_mov_b32_e32 v74, v0
	v_mov_b32_e32 v75, v0
	v_mov_b32_e32 v76, v0
	v_mov_b32_e32 v77, v0
	v_mov_b32_e32 v78, v0
	v_mov_b32_e32 v79, v0
	v_mov_b32_e32 v88, v0
	v_mov_b32_e32 v89, v0
	v_mov_b32_e32 v90, v0
	v_mov_b32_e32 v91, v0
	v_mov_b32_e32 v92, v0
	v_mov_b32_e32 v93, v0
	v_mov_b32_e32 v94, v0
	v_mov_b32_e32 v95, v0
	v_mov_b32_e32 v104, v0
	v_mov_b32_e32 v105, v0
	v_mov_b32_e32 v106, v0
	v_mov_b32_e32 v107, v0
	v_mov_b32_e32 v108, v0
	v_mov_b32_e32 v109, v0
	v_mov_b32_e32 v110, v0
	v_mov_b32_e32 v111, v0
	v_mov_b32_e32 v120, v0
	v_mov_b32_e32 v121, v0
	v_mov_b32_e32 v122, v0
	v_mov_b32_e32 v123, v0
	v_mov_b32_e32 v124, v0
	v_mov_b32_e32 v125, v0
	v_mov_b32_e32 v126, v0
	v_mov_b32_e32 v127, v0
	.p2align 6

;     __device__ __forceinline__ bool next(int i, pg8::Unit& u) const { if (c < 128 || i >= 2) return false; const int idx = (c - 128) * 2 + i; u.pm = idx >> 2; u.pn = idx & 3; return true; }
; template <class Epi, class Sched, bool ALIGN_EPI = false, bool SP2 = false, bool F16 = false>
; __device__ __forceinline__ void gemm_phase(PG8_LAS unsigned char* lds, const Gemm g, const Sched& S, const Epi& E, const int wid_in) {
;     ...
;         const bool has_next = S.next(ui + 1, nxt);
;         const char* nA = has_next ? (const char*)g.A + (size_t)nxt.pm * tstep : cA; const char* nB = has_next ? (const char*)g.Bt + (size_t)nxt.pn * tstep : cB;
;         for (int t = 0; t < nt; t += 2) {
;             const bool last = (t == nt - 2);
;             const char* a1 = cA + (size_t)(t + 1) * kstep;
;             const char* a2 = last ? nA : cA + (size_t)(t + 2) * kstep; const char* b2 = last ? nB : cB + (size_t)(t + 2) * kstep;
;             const char* a3 = a2 + kstep; const char* b3 = b2 + kstep;
;     ...
; #pragma unroll
;         for (int a = 0; a < 2; ++a)
; #pragma unroll
;             for (int b = 0; b < 2; ++b)
; #pragma unroll
;                 for (int m = 0; m < 4; ++m)
; #pragma unroll
;                     for (int n = 0; n < 2; ++n) acc[a][b][m][n] = (f32x4){0.f, 0.f, 0.f, 0.f};
;         cur = nxt; cA = nA; cB = nB; ++ui;
.LBB0_507:
	s_ashr_i32 s27, s26, 31
	s_lshl_b64 s[28:29], s[26:27], 19
	s_add_u32 s28, s15, s28
	s_addc_u32 s29, s40, s29
	s_and_b64 s[30:31], s[8:9], exec
	s_cselect_b32 s10, s29, s45
	s_cselect_b32 s27, s28, s44
	s_ashr_i32 s25, s24, 31
	s_lshl_b64 s[30:31], s[24:25], 19
	s_add_u32 s30, s41, s30
	s_addc_u32 s31, s50, s31
	s_and_b64 s[42:43], s[8:9], exec
	s_cselect_b32 s25, s31, s47
	s_cselect_b32 s35, s30, s46
	s_add_u32 s44, s44, 0x40080
	s_addc_u32 s45, s45, 0
	s_add_u32 s37, s46, 0x100
	v_mov_b32_e32 v0, 0
	s_addc_u32 s42, s47, 0
	s_mov_b32 s43, -2
	v_mov_b32_e32 v1, v0
	v_mov_b32_e32 v2, v0
	v_mov_b32_e32 v3, v0
	v_mov_b32_e32 v4, v0
	v_mov_b32_e32 v5, v0
	v_mov_b32_e32 v6, v0
	v_mov_b32_e32 v7, v0
	v_mov_b32_e32 v16, v0
	v_mov_b32_e32 v17, v0
	v_mov_b32_e32 v18, v0
	v_mov_b32_e32 v19, v0
	v_mov_b32_e32 v20, v0
	v_mov_b32_e32 v21, v0
	v_mov_b32_e32 v22, v0
	v_mov_b32_e32 v23, v0
	v_mov_b32_e32 v32, v0
	v_mov_b32_e32 v33, v0
	v_mov_b32_e32 v34, v0
	v_mov_b32_e32 v35, v0
	v_mov_b32_e32 v36, v0
	v_mov_b32_e32 v37, v0
	v_mov_b32_e32 v38, v0
	v_mov_b32_e32 v39, v0
	v_mov_b32_e32 v48, v0
	v_mov_b32_e32 v49, v0
	v_mov_b32_e32 v50, v0
	v_mov_b32_e32 v51, v0
	v_mov_b32_e32 v52, v0
	v_mov_b32_e32 v53, v0
	v_mov_b32_e32 v54, v0
	v_mov_b32_e32 v55, v0
	v_mov_b32_e32 v8, v0
	v_mov_b32_e32 v9, v0
	v_mov_b32_e32 v10, v0
	v_mov_b32_e32 v11, v0
	v_mov_b32_e32 v12, v0
	v_mov_b32_e32 v13, v0
	v_mov_b32_e32 v14, v0
	v_mov_b32_e32 v15, v0
	v_mov_b32_e32 v24, v0
	v_mov_b32_e32 v25, v0
	v_mov_b32_e32 v26, v0
	v_mov_b32_e32 v27, v0
	v_mov_b32_e32 v28, v0
	v_mov_b32_e32 v29, v0
	v_mov_b32_e32 v30, v0
	v_mov_b32_e32 v31, v0
	v_mov_b32_e32 v40, v0
	v_mov_b32_e32 v41, v0
	v_mov_b32_e32 v42, v0
	v_mov_b32_e32 v43, v0
	v_mov_b32_e32 v44, v0
	v_mov_b32_e32 v45, v0
	v_mov_b32_e32 v46, v0
	v_mov_b32_e32 v47, v0
	v_mov_b32_e32 v56, v0
	v_mov_b32_e32 v57, v0
	v_mov_b32_e32 v58, v0
	v_mov_b32_e32 v59, v0
	v_mov_b32_e32 v60, v0
	v_mov_b32_e32 v61, v0
	v_mov_b32_e32 v62, v0
	v_mov_b32_e32 v63, v0
	v_mov_b32_e32 v64, v0
	v_mov_b32_e32 v65, v0
	v_mov_b32_e32 v66, v0
	v_mov_b32_e32 v67, v0
	v_mov_b32_e32 v68, v0
	v_mov_b32_e32 v69, v0
	v_mov_b32_e32 v70, v0
	v_mov_b32_e32 v71, v0
	v_mov_b32_e32 v80, v0
	v_mov_b32_e32 v81, v0
	v_mov_b32_e32 v82, v0
	v_mov_b32_e32 v83, v0
	v_mov_b32_e32 v84, v0
	v_mov_b32_e32 v85, v0
	v_mov_b32_e32 v86, v0
	v_mov_b32_e32 v87, v0
	v_mov_b32_e32 v96, v0
	v_mov_b32_e32 v97, v0
	v_mov_b32_e32 v98, v0
	v_mov_b32_e32 v99, v0
	v_mov_b32_e32 v100, v0
	v_mov_b32_e32 v101, v0
	v_mov_b32_e32 v102, v0
	v_mov_b32_e32 v103, v0
	v_mov_b32_e32 v112, v0
	v_mov_b32_e32 v113, v0
	v_mov_b32_e32 v114, v0
	v_mov_b32_e32 v115, v0
	v_mov_b32_e32 v116, v0
	v_mov_b32_e32 v117, v0
	v_mov_b32_e32 v118, v0
	v_mov_b32_e32 v119, v0
	v_mov_b32_e32 v72, v0
	v_mov_b32_e32 v73, v0
	v_mov_b32_e32 v74, v0
	v_mov_b32_e32 v75, v0
	v_mov_b32_e32 v76, v0
	v_mov_b32_e32 v77, v0
	v_mov_b32_e32 v78, v0
	v_mov_b32_e32 v79, v0
	v_mov_b32_e32 v88, v0
	v_mov_b32_e32 v89, v0
	v_mov_b32_e32 v90, v0
	v_mov_b32_e32 v91, v0
	v_mov_b32_e32 v92, v0
	v_mov_b32_e32 v93, v0
	v_mov_b32_e32 v94, v0
	v_mov_b32_e32 v95, v0
	v_mov_b32_e32 v104, v0
	v_mov_b32_e32 v105, v0
	v_mov_b32_e32 v106, v0
	v_mov_b32_e32 v107, v0
	v_mov_b32_e32 v108, v0
	v_mov_b32_e32 v109, v0
	v_mov_b32_e32 v110, v0
	v_mov_b32_e32 v111, v0
	v_mov_b32_e32 v120, v0
	v_mov_b32_e32 v121, v0
	v_mov_b32_e32 v122, v0
	v_mov_b32_e32 v123, v0
	v_mov_b32_e32 v124, v0
	v_mov_b32_e32 v125, v0
	v_mov_b32_e32 v126, v0
	v_mov_b32_e32 v127, v0
	.p2align 6

;     __device__ __forceinline__ bool next(int i, pg8::Unit& u) const { if (c < 128 || i >= 2) return false; const int idx = (c - 128) * 2 + i; u.pm = idx >> 2; u.pn = idx & 3; return true; }
; template <class Epi, class Sched, bool ALIGN_EPI = false, bool SP2 = false, bool F16 = false>
; __device__ __forceinline__ void gemm_phase(PG8_LAS unsigned char* lds, const Gemm g, const Sched& S, const Epi& E, const int wid_in) {
;     ...
;         const bool has_next = S.next(ui + 1, nxt);
;         const char* nA = has_next ? (const char*)g.A + (size_t)nxt.pm * tstep : cA; const char* nB = has_next ? (const char*)g.Bt + (size_t)nxt.pn * tstep : cB;
;         for (int t = 0; t < nt; t += 2) {
;             const bool last = (t == nt - 2);
;             const char* a1 = cA + (size_t)(t + 1) * kstep;
;             const char* a2 = last ? nA : cA + (size_t)(t + 2) * kstep; const char* b2 = last ? nB : cB + (size_t)(t + 2) * kstep;
;             const char* a3 = a2 + kstep; const char* b3 = b2 + kstep;
;     ...
; #pragma unroll
;         for (int a = 0; a < 2; ++a)
; #pragma unroll
;             for (int b = 0; b < 2; ++b)
; #pragma unroll
;                 for (int m = 0; m < 4; ++m)
; #pragma unroll
;                     for (int n = 0; n < 2; ++n) acc[a][b][m][n] = (f32x4){0.f, 0.f, 0.f, 0.f};
;         cur = nxt; cA = nA; cB = nB; ++ui;
.LBB0_584:
	s_ashr_i32 s23, s22, 31
	s_lshl_b64 s[24:25], s[22:23], 19
	s_add_u32 s24, s41, s24
	s_addc_u32 s25, s46, s25
	s_and_b64 s[26:27], s[8:9], exec
	s_cselect_b32 s23, s25, s35
	s_cselect_b32 s31, s24, s34
	s_ashr_i32 s21, s20, 31
	s_lshl_b64 s[26:27], s[20:21], 19
	s_add_u32 s26, s47, s26
	s_addc_u32 s27, s48, s27
	s_and_b64 s[42:43], s[8:9], exec
	s_cselect_b32 s21, s27, s37
	s_cselect_b32 s42, s26, s36
	s_add_u32 s34, s34, 0x40080
	s_addc_u32 s35, s35, 0
	s_add_u32 s43, s36, 0x100
	v_mov_b32_e32 v8, 0
	s_addc_u32 s64, s37, 0
	s_mov_b32 s65, -2
	v_mov_b32_e32 v9, v8
	v_mov_b32_e32 v10, v8
	v_mov_b32_e32 v11, v8
	v_mov_b32_e32 v12, v8
	v_mov_b32_e32 v13, v8
	v_mov_b32_e32 v14, v8
	v_mov_b32_e32 v15, v8
	v_mov_b32_e32 v24, v8
	v_mov_b32_e32 v25, v8
	v_mov_b32_e32 v26, v8
	v_mov_b32_e32 v27, v8
	v_mov_b32_e32 v28, v8
	v_mov_b32_e32 v29, v8
	v_mov_b32_e32 v30, v8
	v_mov_b32_e32 v31, v8
	v_mov_b32_e32 v40, v8
	v_mov_b32_e32 v41, v8
	v_mov_b32_e32 v42, v8
	v_mov_b32_e32 v43, v8
	v_mov_b32_e32 v44, v8
	v_mov_b32_e32 v45, v8
	v_mov_b32_e32 v46, v8
	v_mov_b32_e32 v47, v8
	v_mov_b32_e32 v56, v8
	v_mov_b32_e32 v57, v8
	v_mov_b32_e32 v58, v8
	v_mov_b32_e32 v59, v8
	v_mov_b32_e32 v60, v8
	v_mov_b32_e32 v61, v8
	v_mov_b32_e32 v62, v8
	v_mov_b32_e32 v63, v8
	v_mov_b32_e32 v16, v8
	v_mov_b32_e32 v17, v8
	v_mov_b32_e32 v18, v8
	v_mov_b32_e32 v19, v8
	v_mov_b32_e32 v20, v8
	v_mov_b32_e32 v21, v8
	v_mov_b32_e32 v22, v8
	v_mov_b32_e32 v23, v8
	v_mov_b32_e32 v32, v8
	v_mov_b32_e32 v33, v8
	v_mov_b32_e32 v34, v8
	v_mov_b32_e32 v35, v8
	v_mov_b32_e32 v36, v8
	v_mov_b32_e32 v37, v8
	v_mov_b32_e32 v38, v8
	v_mov_b32_e32 v39, v8
	v_mov_b32_e32 v48, v8
	v_mov_b32_e32 v49, v8
	v_mov_b32_e32 v50, v8
	v_mov_b32_e32 v51, v8
	v_mov_b32_e32 v52, v8
	v_mov_b32_e32 v53, v8
	v_mov_b32_e32 v54, v8
	v_mov_b32_e32 v55, v8
	v_mov_b32_e32 v64, v8
	v_mov_b32_e32 v65, v8
	v_mov_b32_e32 v66, v8
	v_mov_b32_e32 v67, v8
	v_mov_b32_e32 v68, v8
	v_mov_b32_e32 v69, v8
	v_mov_b32_e32 v70, v8
	v_mov_b32_e32 v71, v8
	v_mov_b32_e32 v72, v8
	v_mov_b32_e32 v73, v8
	v_mov_b32_e32 v74, v8
	v_mov_b32_e32 v75, v8
	v_mov_b32_e32 v76, v8
	v_mov_b32_e32 v77, v8
	v_mov_b32_e32 v78, v8
	v_mov_b32_e32 v79, v8
	v_mov_b32_e32 v88, v8
	v_mov_b32_e32 v89, v8
	v_mov_b32_e32 v90, v8
	v_mov_b32_e32 v91, v8
	v_mov_b32_e32 v92, v8
	v_mov_b32_e32 v93, v8
	v_mov_b32_e32 v94, v8
	v_mov_b32_e32 v95, v8
	v_mov_b32_e32 v104, v8
	v_mov_b32_e32 v105, v8
	v_mov_b32_e32 v106, v8
	v_mov_b32_e32 v107, v8
	v_mov_b32_e32 v108, v8
	v_mov_b32_e32 v109, v8
	v_mov_b32_e32 v110, v8
	v_mov_b32_e32 v111, v8
	v_mov_b32_e32 v120, v8
	v_mov_b32_e32 v121, v8
	v_mov_b32_e32 v122, v8
	v_mov_b32_e32 v123, v8
	v_mov_b32_e32 v124, v8
	v_mov_b32_e32 v125, v8
	v_mov_b32_e32 v126, v8
	v_mov_b32_e32 v127, v8
	v_mov_b32_e32 v80, v8
	v_mov_b32_e32 v81, v8
	v_mov_b32_e32 v82, v8
	v_mov_b32_e32 v83, v8
	v_mov_b32_e32 v84, v8
	v_mov_b32_e32 v85, v8
	v_mov_b32_e32 v86, v8
	v_mov_b32_e32 v87, v8
	v_mov_b32_e32 v96, v8
	v_mov_b32_e32 v97, v8
	v_mov_b32_e32 v98, v8
	v_mov_b32_e32 v99, v8
	v_mov_b32_e32 v100, v8
	v_mov_b32_e32 v101, v8
	v_mov_b32_e32 v102, v8
	v_mov_b32_e32 v103, v8
	v_mov_b32_e32 v112, v8
	v_mov_b32_e32 v113, v8
	v_mov_b32_e32 v114, v8
	v_mov_b32_e32 v115, v8
	v_mov_b32_e32 v116, v8
	v_mov_b32_e32 v117, v8
	v_mov_b32_e32 v118, v8
	v_mov_b32_e32 v119, v8
	v_mov_b32_e32 v128, v8
	v_mov_b32_e32 v129, v8
	v_mov_b32_e32 v130, v8
	v_mov_b32_e32 v131, v8
	v_mov_b32_e32 v132, v8
	v_mov_b32_e32 v133, v8
	v_mov_b32_e32 v134, v8
	v_mov_b32_e32 v135, v8
	.p2align 6

;     __device__ __forceinline__ bool next(int i, pg8::Unit& u) const { if (c < 128 || i >= 2) return false; const int idx = (c - 128) * 2 + i; u.pm = idx >> 2; u.pn = idx & 3; return true; }
; template <class Epi, class Sched, bool ALIGN_EPI = false, bool SP2 = false, bool F16 = false>
; __device__ __forceinline__ void gemm_phase(PG8_LAS unsigned char* lds, const Gemm g, const Sched& S, const Epi& E, const int wid_in) {
;     ...
;     for (;;) {
;         const bool has_next = S.next(ui + 1, nxt);
;         const char* nA = has_next ? (const char*)g.A + (size_t)nxt.pm * tstep : cA; const char* nB = has_next ? (const char*)g.Bt + (size_t)nxt.pn * tstep : cB;
;         for (int t = 0; t < nt; t += 2) {
.LBB0_618:
	s_mov_b64 s[28:29], 0
	.p2align 6

; template <class Epi, class Sched, bool ALIGN_EPI = false, bool SP2 = false, bool F16 = false>
; __device__ __forceinline__ void gemm_phase(PG8_LAS unsigned char* lds, const Gemm g, const Sched& S, const Epi& E, const int wid_in) {
;     ...
;             const char* a1 = cA + (size_t)(t + 1) * kstep;
;             const char* a2 = last ? nA : cA + (size_t)(t + 2) * kstep; const char* b2 = last ? nB : cB + (size_t)(t + 2) * kstep;
;             const char* a3 = a2 + kstep; const char* b3 = b2 + kstep;
;     ...
; #pragma unroll
;         for (int a = 0; a < 2; ++a)
; #pragma unroll
;             for (int b = 0; b < 2; ++b)
; #pragma unroll
;                 for (int m = 0; m < 4; ++m)
; #pragma unroll
;                     for (int n = 0; n < 2; ++n) acc[a][b][m][n] = (f32x4){0.f, 0.f, 0.f, 0.f};
;         cur = nxt; cA = nA; cB = nB; ++ui;
.LBB0_715:
	s_add_u32 s43, s30, 0x100
	v_mov_b32_e32 v0, 0
	s_addc_u32 s59, s31, 0
	s_mov_b32 s60, -2
	v_mov_b32_e32 v1, v0
	v_mov_b32_e32 v2, v0
	v_mov_b32_e32 v3, v0
	v_mov_b32_e32 v4, v0
	v_mov_b32_e32 v5, v0
	v_mov_b32_e32 v6, v0
	v_mov_b32_e32 v7, v0
	v_mov_b32_e32 v16, v0
	v_mov_b32_e32 v17, v0
	v_mov_b32_e32 v18, v0
	v_mov_b32_e32 v19, v0
	v_mov_b32_e32 v20, v0
	v_mov_b32_e32 v21, v0
	v_mov_b32_e32 v22, v0
	v_mov_b32_e32 v23, v0
	v_mov_b32_e32 v32, v0
	v_mov_b32_e32 v33, v0
	v_mov_b32_e32 v34, v0
	v_mov_b32_e32 v35, v0
	v_mov_b32_e32 v36, v0
	v_mov_b32_e32 v37, v0
	v_mov_b32_e32 v38, v0
	v_mov_b32_e32 v39, v0
	v_mov_b32_e32 v48, v0
	v_mov_b32_e32 v49, v0
	v_mov_b32_e32 v50, v0
	v_mov_b32_e32 v51, v0
	v_mov_b32_e32 v52, v0
	v_mov_b32_e32 v53, v0
	v_mov_b32_e32 v54, v0
	v_mov_b32_e32 v55, v0
	v_mov_b32_e32 v8, v0
	v_mov_b32_e32 v9, v0
	v_mov_b32_e32 v10, v0
	v_mov_b32_e32 v11, v0
	v_mov_b32_e32 v12, v0
	v_mov_b32_e32 v13, v0
	v_mov_b32_e32 v14, v0
	v_mov_b32_e32 v15, v0
	v_mov_b32_e32 v24, v0
	v_mov_b32_e32 v25, v0
	v_mov_b32_e32 v26, v0
	v_mov_b32_e32 v27, v0
	v_mov_b32_e32 v28, v0
	v_mov_b32_e32 v29, v0
	v_mov_b32_e32 v30, v0
	v_mov_b32_e32 v31, v0
	v_mov_b32_e32 v40, v0
	v_mov_b32_e32 v41, v0
	v_mov_b32_e32 v42, v0
	v_mov_b32_e32 v43, v0
	v_mov_b32_e32 v44, v0
	v_mov_b32_e32 v45, v0
	v_mov_b32_e32 v46, v0
	v_mov_b32_e32 v47, v0
	v_mov_b32_e32 v56, v0
	v_mov_b32_e32 v57, v0
	v_mov_b32_e32 v58, v0
	v_mov_b32_e32 v59, v0
	v_mov_b32_e32 v60, v0
	v_mov_b32_e32 v61, v0
	v_mov_b32_e32 v62, v0
	v_mov_b32_e32 v63, v0
	v_mov_b32_e32 v64, v0
	v_mov_b32_e32 v65, v0
	v_mov_b32_e32 v66, v0
	v_mov_b32_e32 v67, v0
	v_mov_b32_e32 v68, v0
	v_mov_b32_e32 v69, v0
	v_mov_b32_e32 v70, v0
	v_mov_b32_e32 v71, v0
	v_mov_b32_e32 v80, v0
	v_mov_b32_e32 v81, v0
	v_mov_b32_e32 v82, v0
	v_mov_b32_e32 v83, v0
	v_mov_b32_e32 v84, v0
	v_mov_b32_e32 v85, v0
	v_mov_b32_e32 v86, v0
	v_mov_b32_e32 v87, v0
	v_mov_b32_e32 v96, v0
	v_mov_b32_e32 v97, v0
	v_mov_b32_e32 v98, v0
	v_mov_b32_e32 v99, v0
	v_mov_b32_e32 v100, v0
	v_mov_b32_e32 v101, v0
	v_mov_b32_e32 v102, v0
	v_mov_b32_e32 v103, v0
	v_mov_b32_e32 v112, v0
	v_mov_b32_e32 v113, v0
	v_mov_b32_e32 v114, v0
	v_mov_b32_e32 v115, v0
	v_mov_b32_e32 v116, v0
	v_mov_b32_e32 v117, v0
	v_mov_b32_e32 v118, v0
	v_mov_b32_e32 v119, v0
	v_mov_b32_e32 v72, v0
	v_mov_b32_e32 v73, v0
	v_mov_b32_e32 v74, v0
	v_mov_b32_e32 v75, v0
	v_mov_b32_e32 v76, v0
	v_mov_b32_e32 v77, v0
	v_mov_b32_e32 v78, v0
	v_mov_b32_e32 v79, v0
	v_mov_b32_e32 v88, v0
	v_mov_b32_e32 v89, v0
	v_mov_b32_e32 v90, v0
	v_mov_b32_e32 v91, v0
	v_mov_b32_e32 v92, v0
	v_mov_b32_e32 v93, v0
	v_mov_b32_e32 v94, v0
	v_mov_b32_e32 v95, v0
	v_mov_b32_e32 v104, v0
	v_mov_b32_e32 v105, v0
	v_mov_b32_e32 v106, v0
	v_mov_b32_e32 v107, v0
	v_mov_b32_e32 v108, v0
	v_mov_b32_e32 v109, v0
	v_mov_b32_e32 v110, v0
	v_mov_b32_e32 v111, v0
	v_mov_b32_e32 v120, v0
	v_mov_b32_e32 v121, v0
	v_mov_b32_e32 v122, v0
	v_mov_b32_e32 v123, v0
	v_mov_b32_e32 v124, v0
	v_mov_b32_e32 v125, v0
	v_mov_b32_e32 v126, v0
	v_mov_b32_e32 v127, v0
	.p2align 6

;     __device__ __forceinline__ bool next(int i, pg8::Unit& u) const { if (c < 128 || i >= 2) return false; const int idx = (c - 128) * 2 + i; u.pm = idx >> 2; u.pn = idx & 3; return true; }
; template <class Epi, class Sched, bool ALIGN_EPI = false, bool SP2 = false, bool F16 = false>
; __device__ __forceinline__ void gemm_phase(PG8_LAS unsigned char* lds, const Gemm g, const Sched& S, const Epi& E, const int wid_in) {
;     ...
;         const bool has_next = S.next(ui + 1, nxt);
;         const char* nA = has_next ? (const char*)g.A + (size_t)nxt.pm * tstep : cA; const char* nB = has_next ? (const char*)g.Bt + (size_t)nxt.pn * tstep : cB;
;         for (int t = 0; t < nt; t += 2) {
;             const bool last = (t == nt - 2);
;             const char* a1 = cA + (size_t)(t + 1) * kstep;
;             const char* a2 = last ? nA : cA + (size_t)(t + 2) * kstep; const char* b2 = last ? nB : cB + (size_t)(t + 2) * kstep;
;             const char* a3 = a2 + kstep; const char* b3 = b2 + kstep;
;     ...
; #pragma unroll
;         for (int a = 0; a < 2; ++a)
; #pragma unroll
;             for (int b = 0; b < 2; ++b)
; #pragma unroll
;                 for (int m = 0; m < 4; ++m)
; #pragma unroll
;                     for (int n = 0; n < 2; ++n) acc[a][b][m][n] = (f32x4){0.f, 0.f, 0.f, 0.f};
;         cur = nxt; cA = nA; cB = nB; ++ui;
.LBB0_811:
	s_ashr_i32 s31, s30, 31
	s_lshl_b64 s[14:15], s[30:31], 19
	s_add_u32 s34, s10, s14
	s_addc_u32 s35, s11, s15
	s_and_b64 s[14:15], s[8:9], exec
	s_cselect_b32 s14, s35, s47
	s_cselect_b32 s15, s34, s46
	s_ashr_i32 s29, s28, 31
	s_lshl_b64 s[36:37], s[28:29], 19
	s_add_u32 s36, s53, s36
	s_addc_u32 s37, s54, s37
	s_and_b64 s[40:41], s[8:9], exec
	s_cselect_b32 s29, s37, s49
	s_cselect_b32 s31, s36, s48
	s_add_u32 s46, s46, 0x40080
	s_addc_u32 s47, s47, 0
	s_add_u32 s40, s48, 0x100
	v_mov_b32_e32 v0, 0
	s_addc_u32 s41, s49, 0
	s_mov_b32 s42, -2
	v_mov_b32_e32 v1, v0
	v_mov_b32_e32 v2, v0
	v_mov_b32_e32 v3, v0
	v_mov_b32_e32 v4, v0
	v_mov_b32_e32 v5, v0
	v_mov_b32_e32 v6, v0
	v_mov_b32_e32 v7, v0
	v_mov_b32_e32 v16, v0
	v_mov_b32_e32 v17, v0
	v_mov_b32_e32 v18, v0
	v_mov_b32_e32 v19, v0
	v_mov_b32_e32 v20, v0
	v_mov_b32_e32 v21, v0
	v_mov_b32_e32 v22, v0
	v_mov_b32_e32 v23, v0
	v_mov_b32_e32 v32, v0
	v_mov_b32_e32 v33, v0
	v_mov_b32_e32 v34, v0
	v_mov_b32_e32 v35, v0
	v_mov_b32_e32 v36, v0
	v_mov_b32_e32 v37, v0
	v_mov_b32_e32 v38, v0
	v_mov_b32_e32 v39, v0
	v_mov_b32_e32 v48, v0
	v_mov_b32_e32 v49, v0
	v_mov_b32_e32 v50, v0
	v_mov_b32_e32 v51, v0
	v_mov_b32_e32 v52, v0
	v_mov_b32_e32 v53, v0
	v_mov_b32_e32 v54, v0
	v_mov_b32_e32 v55, v0
	v_mov_b32_e32 v8, v0
	v_mov_b32_e32 v9, v0
	v_mov_b32_e32 v10, v0
	v_mov_b32_e32 v11, v0
	v_mov_b32_e32 v12, v0
	v_mov_b32_e32 v13, v0
	v_mov_b32_e32 v14, v0
	v_mov_b32_e32 v15, v0
	v_mov_b32_e32 v24, v0
	v_mov_b32_e32 v25, v0
	v_mov_b32_e32 v26, v0
	v_mov_b32_e32 v27, v0
	v_mov_b32_e32 v28, v0
	v_mov_b32_e32 v29, v0
	v_mov_b32_e32 v30, v0
	v_mov_b32_e32 v31, v0
	v_mov_b32_e32 v40, v0
	v_mov_b32_e32 v41, v0
	v_mov_b32_e32 v42, v0
	v_mov_b32_e32 v43, v0
	v_mov_b32_e32 v44, v0
	v_mov_b32_e32 v45, v0
	v_mov_b32_e32 v46, v0
	v_mov_b32_e32 v47, v0
	v_mov_b32_e32 v56, v0
	v_mov_b32_e32 v57, v0
	v_mov_b32_e32 v58, v0
	v_mov_b32_e32 v59, v0
	v_mov_b32_e32 v60, v0
	v_mov_b32_e32 v61, v0
	v_mov_b32_e32 v62, v0
	v_mov_b32_e32 v63, v0
	v_mov_b32_e32 v64, v0
	v_mov_b32_e32 v65, v0
	v_mov_b32_e32 v66, v0
	v_mov_b32_e32 v67, v0
	v_mov_b32_e32 v68, v0
	v_mov_b32_e32 v69, v0
	v_mov_b32_e32 v70, v0
	v_mov_b32_e32 v71, v0
	v_mov_b32_e32 v80, v0
	v_mov_b32_e32 v81, v0
	v_mov_b32_e32 v82, v0
	v_mov_b32_e32 v83, v0
	v_mov_b32_e32 v84, v0
	v_mov_b32_e32 v85, v0
	v_mov_b32_e32 v86, v0
	v_mov_b32_e32 v87, v0
	v_mov_b32_e32 v96, v0
	v_mov_b32_e32 v97, v0
	v_mov_b32_e32 v98, v0
	v_mov_b32_e32 v99, v0
	v_mov_b32_e32 v100, v0
	v_mov_b32_e32 v101, v0
	v_mov_b32_e32 v102, v0
	v_mov_b32_e32 v103, v0
	v_mov_b32_e32 v120, v0
	v_mov_b32_e32 v121, v0
	v_mov_b32_e32 v122, v0
	v_mov_b32_e32 v123, v0
	v_mov_b32_e32 v124, v0
	v_mov_b32_e32 v125, v0
	v_mov_b32_e32 v126, v0
	v_mov_b32_e32 v127, v0
	v_mov_b32_e32 v72, v0
	v_mov_b32_e32 v73, v0
	v_mov_b32_e32 v74, v0
	v_mov_b32_e32 v75, v0
	v_mov_b32_e32 v76, v0
	v_mov_b32_e32 v77, v0
	v_mov_b32_e32 v78, v0
	v_mov_b32_e32 v79, v0
	v_mov_b32_e32 v88, v0
	v_mov_b32_e32 v89, v0
	v_mov_b32_e32 v90, v0
	v_mov_b32_e32 v91, v0
	v_mov_b32_e32 v92, v0
	v_mov_b32_e32 v93, v0
	v_mov_b32_e32 v94, v0
	v_mov_b32_e32 v95, v0
	v_mov_b32_e32 v104, v0
	v_mov_b32_e32 v105, v0
	v_mov_b32_e32 v106, v0
	v_mov_b32_e32 v107, v0
	v_mov_b32_e32 v108, v0
	v_mov_b32_e32 v109, v0
	v_mov_b32_e32 v110, v0
	v_mov_b32_e32 v111, v0
	v_mov_b32_e32 v136, v0
	v_mov_b32_e32 v137, v0
	v_mov_b32_e32 v138, v0
	v_mov_b32_e32 v139, v0
	v_mov_b32_e32 v140, v0
	v_mov_b32_e32 v141, v0
	v_mov_b32_e32 v142, v0
	v_mov_b32_e32 v143, v0
	.p2align 6

;     __device__ __forceinline__ bool next(int i, pg8::Unit& u) const { if (c < 128 || i >= 2) return false; const int idx = (c - 128) * 2 + i; u.pm = idx >> 2; u.pn = idx & 3; return true; }
; template <class Epi, class Sched, bool ALIGN_EPI = false, bool SP2 = false, bool F16 = false>
; __device__ __forceinline__ void gemm_phase(PG8_LAS unsigned char* lds, const Gemm g, const Sched& S, const Epi& E, const int wid_in) {
;     ...
;         const bool has_next = S.next(ui + 1, nxt);
;         const char* nA = has_next ? (const char*)g.A + (size_t)nxt.pm * tstep : cA; const char* nB = has_next ? (const char*)g.Bt + (size_t)nxt.pn * tstep : cB;
;         for (int t = 0; t < nt; t += 2) {
;             const bool last = (t == nt - 2);
;             const char* a1 = cA + (size_t)(t + 1) * kstep;
;             const char* a2 = last ? nA : cA + (size_t)(t + 2) * kstep; const char* b2 = last ? nB : cB + (size_t)(t + 2) * kstep;
;             const char* a3 = a2 + kstep; const char* b3 = b2 + kstep;
;     ...
; #pragma unroll
;         for (int a = 0; a < 2; ++a)
; #pragma unroll
;             for (int b = 0; b < 2; ++b)
; #pragma unroll
;                 for (int m = 0; m < 4; ++m)
; #pragma unroll
;                     for (int n = 0; n < 2; ++n) acc[a][b][m][n] = (f32x4){0.f, 0.f, 0.f, 0.f};
;         cur = nxt; cA = nA; cB = nB; ++ui;
.LBB0_901:
	s_ashr_i32 s35, s34, 31
	s_lshl_b64 s[36:37], s[34:35], 19
	s_add_u32 s36, s61, s36
	s_addc_u32 s37, s62, s37
	s_and_b64 s[42:43], s[8:9], exec
	s_cselect_b32 s11, s37, s47
	s_cselect_b32 s13, s36, s46
	s_ashr_i32 s31, s30, 31
	s_lshl_b64 s[42:43], s[30:31], 19
	s_add_u32 s44, s63, s42
	s_addc_u32 s45, s64, s43
	s_and_b64 s[42:43], s[8:9], exec
	s_cselect_b32 s31, s45, s49
	s_cselect_b32 s35, s44, s48
	s_add_u32 s46, s46, 0x40080
	s_addc_u32 s47, s47, 0
	s_add_u32 s42, s48, 0x100
	v_mov_b32_e32 v0, 0
	s_addc_u32 s43, s49, 0
	s_mov_b32 s52, -2
	s_waitcnt lgkmcnt(0)
	v_mov_b32_e32 v1, v0
	v_mov_b32_e32 v2, v0
	v_mov_b32_e32 v3, v0
	v_mov_b32_e32 v4, v0
	v_mov_b32_e32 v5, v0
	v_mov_b32_e32 v6, v0
	v_mov_b32_e32 v7, v0
	v_mov_b32_e32 v16, v0
	v_mov_b32_e32 v17, v0
	v_mov_b32_e32 v18, v0
	v_mov_b32_e32 v19, v0
	v_mov_b32_e32 v20, v0
	v_mov_b32_e32 v21, v0
	v_mov_b32_e32 v22, v0
	v_mov_b32_e32 v23, v0
	v_mov_b32_e32 v32, v0
	v_mov_b32_e32 v33, v0
	v_mov_b32_e32 v34, v0
	v_mov_b32_e32 v35, v0
	v_mov_b32_e32 v36, v0
	v_mov_b32_e32 v37, v0
	v_mov_b32_e32 v38, v0
	v_mov_b32_e32 v39, v0
	v_mov_b32_e32 v48, v0
	v_mov_b32_e32 v49, v0
	v_mov_b32_e32 v50, v0
	v_mov_b32_e32 v51, v0
	v_mov_b32_e32 v52, v0
	v_mov_b32_e32 v53, v0
	v_mov_b32_e32 v54, v0
	v_mov_b32_e32 v55, v0
	v_mov_b32_e32 v8, v0
	v_mov_b32_e32 v9, v0
	v_mov_b32_e32 v10, v0
	v_mov_b32_e32 v11, v0
	v_mov_b32_e32 v12, v0
	v_mov_b32_e32 v13, v0
	v_mov_b32_e32 v14, v0
	v_mov_b32_e32 v15, v0
	v_mov_b32_e32 v24, v0
	v_mov_b32_e32 v25, v0
	v_mov_b32_e32 v26, v0
	v_mov_b32_e32 v27, v0
	v_mov_b32_e32 v28, v0
	v_mov_b32_e32 v29, v0
	v_mov_b32_e32 v30, v0
	v_mov_b32_e32 v31, v0
	v_mov_b32_e32 v40, v0
	v_mov_b32_e32 v41, v0
	v_mov_b32_e32 v42, v0
	v_mov_b32_e32 v43, v0
	v_mov_b32_e32 v44, v0
	v_mov_b32_e32 v45, v0
	v_mov_b32_e32 v46, v0
	v_mov_b32_e32 v47, v0
	v_mov_b32_e32 v56, v0
	v_mov_b32_e32 v57, v0
	v_mov_b32_e32 v58, v0
	v_mov_b32_e32 v59, v0
	v_mov_b32_e32 v60, v0
	v_mov_b32_e32 v61, v0
	v_mov_b32_e32 v62, v0
	v_mov_b32_e32 v63, v0
	v_mov_b32_e32 v64, v0
	v_mov_b32_e32 v65, v0
	v_mov_b32_e32 v66, v0
	v_mov_b32_e32 v67, v0
	v_mov_b32_e32 v68, v0
	v_mov_b32_e32 v69, v0
	v_mov_b32_e32 v70, v0
	v_mov_b32_e32 v71, v0
	v_mov_b32_e32 v80, v0
	v_mov_b32_e32 v81, v0
	v_mov_b32_e32 v82, v0
	v_mov_b32_e32 v83, v0
	v_mov_b32_e32 v84, v0
	v_mov_b32_e32 v85, v0
	v_mov_b32_e32 v86, v0
	v_mov_b32_e32 v87, v0
	v_mov_b32_e32 v96, v0
	v_mov_b32_e32 v97, v0
	v_mov_b32_e32 v98, v0
	v_mov_b32_e32 v99, v0
	v_mov_b32_e32 v100, v0
	v_mov_b32_e32 v101, v0
	v_mov_b32_e32 v102, v0
	v_mov_b32_e32 v103, v0
	v_mov_b32_e32 v112, v0
	v_mov_b32_e32 v113, v0
	v_mov_b32_e32 v114, v0
	v_mov_b32_e32 v115, v0
	v_mov_b32_e32 v116, v0
	v_mov_b32_e32 v117, v0
	v_mov_b32_e32 v118, v0
	v_mov_b32_e32 v119, v0
	v_mov_b32_e32 v72, v0
	v_mov_b32_e32 v73, v0
	v_mov_b32_e32 v74, v0
	v_mov_b32_e32 v75, v0
	v_mov_b32_e32 v76, v0
	v_mov_b32_e32 v77, v0
	v_mov_b32_e32 v78, v0
	v_mov_b32_e32 v79, v0
	v_mov_b32_e32 v88, v0
	v_mov_b32_e32 v89, v0
	v_mov_b32_e32 v90, v0
	v_mov_b32_e32 v91, v0
	v_mov_b32_e32 v92, v0
	v_mov_b32_e32 v93, v0
	v_mov_b32_e32 v94, v0
	v_mov_b32_e32 v95, v0
	v_mov_b32_e32 v104, v0
	v_mov_b32_e32 v105, v0
	v_mov_b32_e32 v106, v0
	v_mov_b32_e32 v107, v0
	v_mov_b32_e32 v108, v0
	v_mov_b32_e32 v109, v0
	v_mov_b32_e32 v110, v0
	v_mov_b32_e32 v111, v0
	v_mov_b32_e32 v120, v0
	v_mov_b32_e32 v121, v0
	v_mov_b32_e32 v122, v0
	v_mov_b32_e32 v123, v0
	v_mov_b32_e32 v124, v0
	v_mov_b32_e32 v125, v0
	v_mov_b32_e32 v126, v0
	v_mov_b32_e32 v127, v0
	.p2align 6

; template <int MODE> __device__ __forceinline__ void attn_unit(int b, int h, int qb, int t_lo, const bf16_t* Q, const bf16_t* __restrict__ K, const bf16_t* __restrict__ V, bf16_t* O, ATT_LAS unsigned char* lds, const int wid, const float kn2, const float bmax) {
;     ...
; #pragma unroll 1
;     for (int j = 0; j < n - 1; ++j) ATT_ITER(j, true, true);
.LBB0_1059:
.LBB0_1060:
.LBB0_1062:
	.p2align 6

;     __device__ __forceinline__ bool next(int i, pg8::Unit& u) const { if (c < 128 || i >= 2) return false; const int idx = (c - 128) * 2 + i; u.pm = idx >> 2; u.pn = idx & 3; return true; }
; template <class Epi, class Sched, bool ALIGN_EPI = false, bool SP2 = false, bool F16 = false>
; __device__ __forceinline__ void gemm_phase(PG8_LAS unsigned char* lds, const Gemm g, const Sched& S, const Epi& E, const int wid_in) {
;     ...
;         const bool has_next = S.next(ui + 1, nxt);
;         const char* nA = has_next ? (const char*)g.A + (size_t)nxt.pm * tstep : cA; const char* nB = has_next ? (const char*)g.Bt + (size_t)nxt.pn * tstep : cB;
;         for (int t = 0; t < nt; t += 2) {
;             const bool last = (t == nt - 2);
;             const char* a1 = cA + (size_t)(t + 1) * kstep;
;             const char* a2 = last ? nA : cA + (size_t)(t + 2) * kstep; const char* b2 = last ? nB : cB + (size_t)(t + 2) * kstep;
;             const char* a3 = a2 + kstep; const char* b3 = b2 + kstep;
;     ...
; #pragma unroll
;         for (int a = 0; a < 2; ++a)
; #pragma unroll
;             for (int b = 0; b < 2; ++b)
; #pragma unroll
;                 for (int m = 0; m < 4; ++m)
; #pragma unroll
;                     for (int n = 0; n < 2; ++n) acc[a][b][m][n] = (f32x4){0.f, 0.f, 0.f, 0.f};
;         cur = nxt; cA = nA; cB = nB; ++ui;
.LBB0_1164:
	s_ashr_i32 s35, s34, 31
	s_lshl_b64 s[36:37], s[34:35], 19
	s_add_u32 s36, s15, s36
	s_addc_u32 s37, s19, s37
	s_and_b64 s[42:43], s[10:11], exec
	s_cselect_b32 s35, s37, s49
	s_cselect_b32 s42, s36, s48
	s_ashr_i32 s31, s30, 31
	s_lshl_b64 s[44:45], s[30:31], 19
	s_add_u32 s44, s21, s44
	s_addc_u32 s45, s40, s45
	s_and_b64 s[52:53], s[10:11], exec
	s_cselect_b32 s31, s45, s51
	s_cselect_b32 s43, s44, s50
	s_add_u32 s48, s48, 0x40080
	s_addc_u32 s49, s49, 0
	s_add_u32 s47, s50, 0x100
	v_mov_b32_e32 v0, 0
	s_addc_u32 s63, s51, 0
	s_mov_b32 s64, -2
	v_mov_b32_e32 v1, v0
	v_mov_b32_e32 v2, v0
	v_mov_b32_e32 v3, v0
	v_mov_b32_e32 v4, v0
	v_mov_b32_e32 v5, v0
	v_mov_b32_e32 v6, v0
	v_mov_b32_e32 v7, v0
	v_mov_b32_e32 v16, v0
	v_mov_b32_e32 v17, v0
	v_mov_b32_e32 v18, v0
	v_mov_b32_e32 v19, v0
	v_mov_b32_e32 v20, v0
	v_mov_b32_e32 v21, v0
	v_mov_b32_e32 v22, v0
	v_mov_b32_e32 v23, v0
	v_mov_b32_e32 v32, v0
	v_mov_b32_e32 v33, v0
	v_mov_b32_e32 v34, v0
	v_mov_b32_e32 v35, v0
	v_mov_b32_e32 v36, v0
	v_mov_b32_e32 v37, v0
	v_mov_b32_e32 v38, v0
	v_mov_b32_e32 v39, v0
	v_mov_b32_e32 v48, v0
	v_mov_b32_e32 v49, v0
	v_mov_b32_e32 v50, v0
	v_mov_b32_e32 v51, v0
	v_mov_b32_e32 v52, v0
	v_mov_b32_e32 v53, v0
	v_mov_b32_e32 v54, v0
	v_mov_b32_e32 v55, v0
	v_mov_b32_e32 v8, v0
	v_mov_b32_e32 v9, v0
	v_mov_b32_e32 v10, v0
	v_mov_b32_e32 v11, v0
	v_mov_b32_e32 v12, v0
	v_mov_b32_e32 v13, v0
	v_mov_b32_e32 v14, v0
	v_mov_b32_e32 v15, v0
	v_mov_b32_e32 v24, v0
	v_mov_b32_e32 v25, v0
	v_mov_b32_e32 v26, v0
	v_mov_b32_e32 v27, v0
	v_mov_b32_e32 v28, v0
	v_mov_b32_e32 v29, v0
	v_mov_b32_e32 v30, v0
	v_mov_b32_e32 v31, v0
	v_mov_b32_e32 v40, v0
	v_mov_b32_e32 v41, v0
	v_mov_b32_e32 v42, v0
	v_mov_b32_e32 v43, v0
	v_mov_b32_e32 v44, v0
	v_mov_b32_e32 v45, v0
	v_mov_b32_e32 v46, v0
	v_mov_b32_e32 v47, v0
	v_mov_b32_e32 v56, v0
	v_mov_b32_e32 v57, v0
	v_mov_b32_e32 v58, v0
	v_mov_b32_e32 v59, v0
	v_mov_b32_e32 v60, v0
	v_mov_b32_e32 v61, v0
	v_mov_b32_e32 v62, v0
	v_mov_b32_e32 v63, v0
	v_mov_b32_e32 v64, v0
	v_mov_b32_e32 v65, v0
	v_mov_b32_e32 v66, v0
	v_mov_b32_e32 v67, v0
	v_mov_b32_e32 v68, v0
	v_mov_b32_e32 v69, v0
	v_mov_b32_e32 v70, v0
	v_mov_b32_e32 v71, v0
	v_mov_b32_e32 v80, v0
	v_mov_b32_e32 v81, v0
	v_mov_b32_e32 v82, v0
	v_mov_b32_e32 v83, v0
	v_mov_b32_e32 v84, v0
	v_mov_b32_e32 v85, v0
	v_mov_b32_e32 v86, v0
	v_mov_b32_e32 v87, v0
	v_mov_b32_e32 v96, v0
	v_mov_b32_e32 v97, v0
	v_mov_b32_e32 v98, v0
	v_mov_b32_e32 v99, v0
	v_mov_b32_e32 v100, v0
	v_mov_b32_e32 v101, v0
	v_mov_b32_e32 v102, v0
	v_mov_b32_e32 v103, v0
	v_mov_b32_e32 v112, v0
	v_mov_b32_e32 v113, v0
	v_mov_b32_e32 v114, v0
	v_mov_b32_e32 v115, v0
	v_mov_b32_e32 v116, v0
	v_mov_b32_e32 v117, v0
	v_mov_b32_e32 v118, v0
	v_mov_b32_e32 v119, v0
	v_mov_b32_e32 v72, v0
	v_mov_b32_e32 v73, v0
	v_mov_b32_e32 v74, v0
	v_mov_b32_e32 v75, v0
	v_mov_b32_e32 v76, v0
	v_mov_b32_e32 v77, v0
	v_mov_b32_e32 v78, v0
	v_mov_b32_e32 v79, v0
	v_mov_b32_e32 v88, v0
	v_mov_b32_e32 v89, v0
	v_mov_b32_e32 v90, v0
	v_mov_b32_e32 v91, v0
	v_mov_b32_e32 v92, v0
	v_mov_b32_e32 v93, v0
	v_mov_b32_e32 v94, v0
	v_mov_b32_e32 v95, v0
	v_mov_b32_e32 v104, v0
	v_mov_b32_e32 v105, v0
	v_mov_b32_e32 v106, v0
	v_mov_b32_e32 v107, v0
	v_mov_b32_e32 v108, v0
	v_mov_b32_e32 v109, v0
	v_mov_b32_e32 v110, v0
	v_mov_b32_e32 v111, v0
	v_mov_b32_e32 v120, v0
	v_mov_b32_e32 v121, v0
	v_mov_b32_e32 v122, v0
	v_mov_b32_e32 v123, v0
	v_mov_b32_e32 v124, v0
	v_mov_b32_e32 v125, v0
	v_mov_b32_e32 v126, v0
	v_mov_b32_e32 v127, v0
	.p2align 6

;     __device__ __forceinline__ bool next(int i, pg8::Unit& u) const { if (c < 128 || i >= 2) return false; const int idx = (c - 128) * 2 + i; u.pm = idx >> 2; u.pn = idx & 3; return true; }
; template <class Epi, class Sched, bool ALIGN_EPI = false, bool SP2 = false, bool F16 = false>
; __device__ __forceinline__ void gemm_phase(PG8_LAS unsigned char* lds, const Gemm g, const Sched& S, const Epi& E, const int wid_in) {
;     ...
;         const bool has_next = S.next(ui + 1, nxt);
;         const char* nA = has_next ? (const char*)g.A + (size_t)nxt.pm * tstep : cA; const char* nB = has_next ? (const char*)g.Bt + (size_t)nxt.pn * tstep : cB;
;         for (int t = 0; t < nt; t += 2) {
;             const bool last = (t == nt - 2);
;             const char* a1 = cA + (size_t)(t + 1) * kstep;
;             const char* a2 = last ? nA : cA + (size_t)(t + 2) * kstep; const char* b2 = last ? nB : cB + (size_t)(t + 2) * kstep;
;             const char* a3 = a2 + kstep; const char* b3 = b2 + kstep;
;     ...
; #pragma unroll
;         for (int a = 0; a < 2; ++a)
; #pragma unroll
;             for (int b = 0; b < 2; ++b)
; #pragma unroll
;                 for (int m = 0; m < 4; ++m)
; #pragma unroll
;                     for (int n = 0; n < 2; ++n) acc[a][b][m][n] = (f32x4){0.f, 0.f, 0.f, 0.f};
;         cur = nxt; cA = nA; cB = nB; ++ui;
.LBB0_1241:
	s_ashr_i32 s29, s28, 31
	s_lshl_b64 s[30:31], s[28:29], 19
	s_add_u32 s30, s21, s30
	s_addc_u32 s31, s40, s31
	s_and_b64 s[34:35], s[10:11], exec
	s_cselect_b32 s29, s31, s47
	s_cselect_b32 s42, s30, s46
	s_ashr_i32 s27, s26, 31
	s_lshl_b64 s[34:35], s[26:27], 19
	s_add_u32 s34, s41, s34
	s_addc_u32 s35, s52, s35
	s_and_b64 s[50:51], s[10:11], exec
	s_cselect_b32 s27, s35, s49
	s_cselect_b32 s43, s34, s48
	s_add_u32 s46, s46, 0x40080
	s_addc_u32 s47, s47, 0
	s_add_u32 s45, s48, 0x100
	v_mov_b32_e32 v8, 0
	s_addc_u32 s66, s49, 0
	s_mov_b32 s67, -2
	v_mov_b32_e32 v9, v8
	v_mov_b32_e32 v10, v8
	v_mov_b32_e32 v11, v8
	v_mov_b32_e32 v12, v8
	v_mov_b32_e32 v13, v8
	v_mov_b32_e32 v14, v8
	v_mov_b32_e32 v15, v8
	v_mov_b32_e32 v24, v8
	v_mov_b32_e32 v25, v8
	v_mov_b32_e32 v26, v8
	v_mov_b32_e32 v27, v8
	v_mov_b32_e32 v28, v8
	v_mov_b32_e32 v29, v8
	v_mov_b32_e32 v30, v8
	v_mov_b32_e32 v31, v8
	v_mov_b32_e32 v40, v8
	v_mov_b32_e32 v41, v8
	v_mov_b32_e32 v42, v8
	v_mov_b32_e32 v43, v8
	v_mov_b32_e32 v44, v8
	v_mov_b32_e32 v45, v8
	v_mov_b32_e32 v46, v8
	v_mov_b32_e32 v47, v8
	v_mov_b32_e32 v56, v8
	v_mov_b32_e32 v57, v8
	v_mov_b32_e32 v58, v8
	v_mov_b32_e32 v59, v8
	v_mov_b32_e32 v60, v8
	v_mov_b32_e32 v61, v8
	v_mov_b32_e32 v62, v8
	v_mov_b32_e32 v63, v8
	v_mov_b32_e32 v16, v8
	v_mov_b32_e32 v17, v8
	v_mov_b32_e32 v18, v8
	v_mov_b32_e32 v19, v8
	v_mov_b32_e32 v20, v8
	v_mov_b32_e32 v21, v8
	v_mov_b32_e32 v22, v8
	v_mov_b32_e32 v23, v8
	v_mov_b32_e32 v32, v8
	v_mov_b32_e32 v33, v8
	v_mov_b32_e32 v34, v8
	v_mov_b32_e32 v35, v8
	v_mov_b32_e32 v36, v8
	v_mov_b32_e32 v37, v8
	v_mov_b32_e32 v38, v8
	v_mov_b32_e32 v39, v8
	v_mov_b32_e32 v48, v8
	v_mov_b32_e32 v49, v8
	v_mov_b32_e32 v50, v8
	v_mov_b32_e32 v51, v8
	v_mov_b32_e32 v52, v8
	v_mov_b32_e32 v53, v8
	v_mov_b32_e32 v54, v8
	v_mov_b32_e32 v55, v8
	v_mov_b32_e32 v64, v8
	v_mov_b32_e32 v65, v8
	v_mov_b32_e32 v66, v8
	v_mov_b32_e32 v67, v8
	v_mov_b32_e32 v68, v8
	v_mov_b32_e32 v69, v8
	v_mov_b32_e32 v70, v8
	v_mov_b32_e32 v71, v8
	v_mov_b32_e32 v72, v8
	v_mov_b32_e32 v73, v8
	v_mov_b32_e32 v74, v8
	v_mov_b32_e32 v75, v8
	v_mov_b32_e32 v76, v8
	v_mov_b32_e32 v77, v8
	v_mov_b32_e32 v78, v8
	v_mov_b32_e32 v79, v8
	v_mov_b32_e32 v88, v8
	v_mov_b32_e32 v89, v8
	v_mov_b32_e32 v90, v8
	v_mov_b32_e32 v91, v8
	v_mov_b32_e32 v92, v8
	v_mov_b32_e32 v93, v8
	v_mov_b32_e32 v94, v8
	v_mov_b32_e32 v95, v8
	v_mov_b32_e32 v104, v8
	v_mov_b32_e32 v105, v8
	v_mov_b32_e32 v106, v8
	v_mov_b32_e32 v107, v8
	v_mov_b32_e32 v108, v8
	v_mov_b32_e32 v109, v8
	v_mov_b32_e32 v110, v8
	v_mov_b32_e32 v111, v8
	v_mov_b32_e32 v120, v8
	v_mov_b32_e32 v121, v8
	v_mov_b32_e32 v122, v8
	v_mov_b32_e32 v123, v8
	v_mov_b32_e32 v124, v8
	v_mov_b32_e32 v125, v8
	v_mov_b32_e32 v126, v8
	v_mov_b32_e32 v127, v8
	v_mov_b32_e32 v80, v8
	v_mov_b32_e32 v81, v8
	v_mov_b32_e32 v82, v8
	v_mov_b32_e32 v83, v8
	v_mov_b32_e32 v84, v8
	v_mov_b32_e32 v85, v8
	v_mov_b32_e32 v86, v8
	v_mov_b32_e32 v87, v8
	v_mov_b32_e32 v96, v8
	v_mov_b32_e32 v97, v8
	v_mov_b32_e32 v98, v8
	v_mov_b32_e32 v99, v8
	v_mov_b32_e32 v100, v8
	v_mov_b32_e32 v101, v8
	v_mov_b32_e32 v102, v8
	v_mov_b32_e32 v103, v8
	v_mov_b32_e32 v112, v8
	v_mov_b32_e32 v113, v8
	v_mov_b32_e32 v114, v8
	v_mov_b32_e32 v115, v8
	v_mov_b32_e32 v116, v8
	v_mov_b32_e32 v117, v8
	v_mov_b32_e32 v118, v8
	v_mov_b32_e32 v119, v8
	v_mov_b32_e32 v128, v8
	v_mov_b32_e32 v129, v8
	v_mov_b32_e32 v130, v8
	v_mov_b32_e32 v131, v8
	v_mov_b32_e32 v132, v8
	v_mov_b32_e32 v133, v8
	v_mov_b32_e32 v134, v8
	v_mov_b32_e32 v135, v8
	.p2align 6

;     __device__ __forceinline__ bool next(int i, pg8::Unit& u) const { if (c < 128 || i >= 2) return false; const int idx = (c - 128) * 2 + i; u.pm = idx >> 2; u.pn = idx & 3; return true; }
; template <class Epi, class Sched, bool ALIGN_EPI = false, bool SP2 = false, bool F16 = false>
; __device__ __forceinline__ void gemm_phase(PG8_LAS unsigned char* lds, const Gemm g, const Sched& S, const Epi& E, const int wid_in) {
;     ...
;     for (;;) {
;         const bool has_next = S.next(ui + 1, nxt);
;         const char* nA = has_next ? (const char*)g.A + (size_t)nxt.pm * tstep : cA; const char* nB = has_next ? (const char*)g.Bt + (size_t)nxt.pn * tstep : cB;
;         for (int t = 0; t < nt; t += 2) {
.LBB0_1275:
	s_mov_b64 s[34:35], 0
	.p2align 6

; template <class Epi, class Sched, bool ALIGN_EPI = false, bool SP2 = false, bool F16 = false>
; __device__ __forceinline__ void gemm_phase(PG8_LAS unsigned char* lds, const Gemm g, const Sched& S, const Epi& E, const int wid_in) {
;     ...
;             const char* a1 = cA + (size_t)(t + 1) * kstep;
;             const char* a2 = last ? nA : cA + (size_t)(t + 2) * kstep; const char* b2 = last ? nB : cB + (size_t)(t + 2) * kstep;
;             const char* a3 = a2 + kstep; const char* b3 = b2 + kstep;
;     ...
; #pragma unroll
;         for (int a = 0; a < 2; ++a)
; #pragma unroll
;             for (int b = 0; b < 2; ++b)
; #pragma unroll
;                 for (int m = 0; m < 4; ++m)
; #pragma unroll
;                     for (int n = 0; n < 2; ++n) acc[a][b][m][n] = (f32x4){0.f, 0.f, 0.f, 0.f};
;         cur = nxt; cA = nA; cB = nB; ++ui;
.LBB0_1372:
	s_add_u32 s43, s44, 0x100
	v_mov_b32_e32 v0, 0
	s_addc_u32 s61, s45, 0
	s_mov_b32 s62, -2
	v_mov_b32_e32 v1, v0
	v_mov_b32_e32 v2, v0
	v_mov_b32_e32 v3, v0
	v_mov_b32_e32 v4, v0
	v_mov_b32_e32 v5, v0
	v_mov_b32_e32 v6, v0
	v_mov_b32_e32 v7, v0
	v_mov_b32_e32 v16, v0
	v_mov_b32_e32 v17, v0
	v_mov_b32_e32 v18, v0
	v_mov_b32_e32 v19, v0
	v_mov_b32_e32 v20, v0
	v_mov_b32_e32 v21, v0
	v_mov_b32_e32 v22, v0
	v_mov_b32_e32 v23, v0
	v_mov_b32_e32 v32, v0
	v_mov_b32_e32 v33, v0
	v_mov_b32_e32 v34, v0
	v_mov_b32_e32 v35, v0
	v_mov_b32_e32 v36, v0
	v_mov_b32_e32 v37, v0
	v_mov_b32_e32 v38, v0
	v_mov_b32_e32 v39, v0
	v_mov_b32_e32 v48, v0
	v_mov_b32_e32 v49, v0
	v_mov_b32_e32 v50, v0
	v_mov_b32_e32 v51, v0
	v_mov_b32_e32 v52, v0
	v_mov_b32_e32 v53, v0
	v_mov_b32_e32 v54, v0
	v_mov_b32_e32 v55, v0
	v_mov_b32_e32 v8, v0
	v_mov_b32_e32 v9, v0
	v_mov_b32_e32 v10, v0
	v_mov_b32_e32 v11, v0
	v_mov_b32_e32 v12, v0
	v_mov_b32_e32 v13, v0
	v_mov_b32_e32 v14, v0
	v_mov_b32_e32 v15, v0
	v_mov_b32_e32 v24, v0
	v_mov_b32_e32 v25, v0
	v_mov_b32_e32 v26, v0
	v_mov_b32_e32 v27, v0
	v_mov_b32_e32 v28, v0
	v_mov_b32_e32 v29, v0
	v_mov_b32_e32 v30, v0
	v_mov_b32_e32 v31, v0
	v_mov_b32_e32 v40, v0
	v_mov_b32_e32 v41, v0
	v_mov_b32_e32 v42, v0
	v_mov_b32_e32 v43, v0
	v_mov_b32_e32 v44, v0
	v_mov_b32_e32 v45, v0
	v_mov_b32_e32 v46, v0
	v_mov_b32_e32 v47, v0
	v_mov_b32_e32 v56, v0
	v_mov_b32_e32 v57, v0
	v_mov_b32_e32 v58, v0
	v_mov_b32_e32 v59, v0
	v_mov_b32_e32 v60, v0
	v_mov_b32_e32 v61, v0
	v_mov_b32_e32 v62, v0
	v_mov_b32_e32 v63, v0
	v_mov_b32_e32 v64, v0
	v_mov_b32_e32 v65, v0
	v_mov_b32_e32 v66, v0
	v_mov_b32_e32 v67, v0
	v_mov_b32_e32 v68, v0
	v_mov_b32_e32 v69, v0
	v_mov_b32_e32 v70, v0
	v_mov_b32_e32 v71, v0
	v_mov_b32_e32 v80, v0
	v_mov_b32_e32 v81, v0
	v_mov_b32_e32 v82, v0
	v_mov_b32_e32 v83, v0
	v_mov_b32_e32 v84, v0
	v_mov_b32_e32 v85, v0
	v_mov_b32_e32 v86, v0
	v_mov_b32_e32 v87, v0
	v_mov_b32_e32 v96, v0
	v_mov_b32_e32 v97, v0
	v_mov_b32_e32 v98, v0
	v_mov_b32_e32 v99, v0
	v_mov_b32_e32 v100, v0
	v_mov_b32_e32 v101, v0
	v_mov_b32_e32 v102, v0
	v_mov_b32_e32 v103, v0
	v_mov_b32_e32 v112, v0
	v_mov_b32_e32 v113, v0
	v_mov_b32_e32 v114, v0
	v_mov_b32_e32 v115, v0
	v_mov_b32_e32 v116, v0
	v_mov_b32_e32 v117, v0
	v_mov_b32_e32 v118, v0
	v_mov_b32_e32 v119, v0
	v_mov_b32_e32 v72, v0
	v_mov_b32_e32 v73, v0
	v_mov_b32_e32 v74, v0
	v_mov_b32_e32 v75, v0
	v_mov_b32_e32 v76, v0
	v_mov_b32_e32 v77, v0
	v_mov_b32_e32 v78, v0
	v_mov_b32_e32 v79, v0
	v_mov_b32_e32 v88, v0
	v_mov_b32_e32 v89, v0
	v_mov_b32_e32 v90, v0
	v_mov_b32_e32 v91, v0
	v_mov_b32_e32 v92, v0
	v_mov_b32_e32 v93, v0
	v_mov_b32_e32 v94, v0
	v_mov_b32_e32 v95, v0
	v_mov_b32_e32 v104, v0
	v_mov_b32_e32 v105, v0
	v_mov_b32_e32 v106, v0
	v_mov_b32_e32 v107, v0
	v_mov_b32_e32 v108, v0
	v_mov_b32_e32 v109, v0
	v_mov_b32_e32 v110, v0
	v_mov_b32_e32 v111, v0
	v_mov_b32_e32 v120, v0
	v_mov_b32_e32 v121, v0
	v_mov_b32_e32 v122, v0
	v_mov_b32_e32 v123, v0
	v_mov_b32_e32 v124, v0
	v_mov_b32_e32 v125, v0
	v_mov_b32_e32 v126, v0
	v_mov_b32_e32 v127, v0
	.p2align 6

;     __device__ __forceinline__ bool next(int i, pg8::Unit& u) const { if (c < 128 || i >= 2) return false; const int idx = (c - 128) * 2 + i; u.pm = idx >> 2; u.pn = idx & 3; return true; }
; template <class Epi, class Sched, bool ALIGN_EPI = false, bool SP2 = false, bool F16 = false>
; __device__ __forceinline__ void gemm_phase(PG8_LAS unsigned char* lds, const Gemm g, const Sched& S, const Epi& E, const int wid_in) {
;     ...
;         const bool has_next = S.next(ui + 1, nxt);
;         const char* nA = has_next ? (const char*)g.A + (size_t)nxt.pm * tstep : cA; const char* nB = has_next ? (const char*)g.Bt + (size_t)nxt.pn * tstep : cB;
;         for (int t = 0; t < nt; t += 2) {
;             const bool last = (t == nt - 2);
;             const char* a1 = cA + (size_t)(t + 1) * kstep;
;             const char* a2 = last ? nA : cA + (size_t)(t + 2) * kstep; const char* b2 = last ? nB : cB + (size_t)(t + 2) * kstep;
;             const char* a3 = a2 + kstep; const char* b3 = b2 + kstep;
;     ...
; #pragma unroll
;         for (int a = 0; a < 2; ++a)
; #pragma unroll
;             for (int b = 0; b < 2; ++b)
; #pragma unroll
;                 for (int m = 0; m < 4; ++m)
; #pragma unroll
;                     for (int n = 0; n < 2; ++n) acc[a][b][m][n] = (f32x4){0.f, 0.f, 0.f, 0.f};
;         cur = nxt; cA = nA; cB = nB; ++ui;
.LBB0_1468:
	s_ashr_i32 s45, s44, 31
	s_lshl_b64 s[14:15], s[44:45], 19
	s_add_u32 s46, s12, s14
	s_addc_u32 s47, s13, s15
	s_and_b64 s[14:15], s[10:11], exec
	s_cselect_b32 s14, s47, s53
	s_cselect_b32 s15, s46, s52
	s_ashr_i32 s37, s36, 31
	s_lshl_b64 s[40:41], s[36:37], 19
	s_add_u32 s48, s21, s40
	s_addc_u32 s49, s58, s41
	s_and_b64 s[40:41], s[10:11], exec
	s_cselect_b32 s37, s49, s55
	s_cselect_b32 s40, s48, s54
	s_add_u32 s52, s52, 0x40080
	s_addc_u32 s53, s53, 0
	s_add_u32 s41, s54, 0x100
	v_mov_b32_e32 v0, 0
	s_addc_u32 s42, s55, 0
	s_mov_b32 s43, -2
	v_mov_b32_e32 v1, v0
	v_mov_b32_e32 v2, v0
	v_mov_b32_e32 v3, v0
	v_mov_b32_e32 v4, v0
	v_mov_b32_e32 v5, v0
	v_mov_b32_e32 v6, v0
	v_mov_b32_e32 v7, v0
	v_mov_b32_e32 v16, v0
	v_mov_b32_e32 v17, v0
	v_mov_b32_e32 v18, v0
	v_mov_b32_e32 v19, v0
	v_mov_b32_e32 v20, v0
	v_mov_b32_e32 v21, v0
	v_mov_b32_e32 v22, v0
	v_mov_b32_e32 v23, v0
	v_mov_b32_e32 v32, v0
	v_mov_b32_e32 v33, v0
	v_mov_b32_e32 v34, v0
	v_mov_b32_e32 v35, v0
	v_mov_b32_e32 v36, v0
	v_mov_b32_e32 v37, v0
	v_mov_b32_e32 v38, v0
	v_mov_b32_e32 v39, v0
	v_mov_b32_e32 v48, v0
	v_mov_b32_e32 v49, v0
	v_mov_b32_e32 v50, v0
	v_mov_b32_e32 v51, v0
	v_mov_b32_e32 v52, v0
	v_mov_b32_e32 v53, v0
	v_mov_b32_e32 v54, v0
	v_mov_b32_e32 v55, v0
	v_mov_b32_e32 v8, v0
	v_mov_b32_e32 v9, v0
	v_mov_b32_e32 v10, v0
	v_mov_b32_e32 v11, v0
	v_mov_b32_e32 v12, v0
	v_mov_b32_e32 v13, v0
	v_mov_b32_e32 v14, v0
	v_mov_b32_e32 v15, v0
	v_mov_b32_e32 v24, v0
	v_mov_b32_e32 v25, v0
	v_mov_b32_e32 v26, v0
	v_mov_b32_e32 v27, v0
	v_mov_b32_e32 v28, v0
	v_mov_b32_e32 v29, v0
	v_mov_b32_e32 v30, v0
	v_mov_b32_e32 v31, v0
	v_mov_b32_e32 v40, v0
	v_mov_b32_e32 v41, v0
	v_mov_b32_e32 v42, v0
	v_mov_b32_e32 v43, v0
	v_mov_b32_e32 v44, v0
	v_mov_b32_e32 v45, v0
	v_mov_b32_e32 v46, v0
	v_mov_b32_e32 v47, v0
	v_mov_b32_e32 v56, v0
	v_mov_b32_e32 v57, v0
	v_mov_b32_e32 v58, v0
	v_mov_b32_e32 v59, v0
	v_mov_b32_e32 v60, v0
	v_mov_b32_e32 v61, v0
	v_mov_b32_e32 v62, v0
	v_mov_b32_e32 v63, v0
	v_mov_b32_e32 v64, v0
	v_mov_b32_e32 v65, v0
	v_mov_b32_e32 v66, v0
	v_mov_b32_e32 v67, v0
	v_mov_b32_e32 v68, v0
	v_mov_b32_e32 v69, v0
	v_mov_b32_e32 v70, v0
	v_mov_b32_e32 v71, v0
	v_mov_b32_e32 v80, v0
	v_mov_b32_e32 v81, v0
	v_mov_b32_e32 v82, v0
	v_mov_b32_e32 v83, v0
	v_mov_b32_e32 v84, v0
	v_mov_b32_e32 v85, v0
	v_mov_b32_e32 v86, v0
	v_mov_b32_e32 v87, v0
	v_mov_b32_e32 v96, v0
	v_mov_b32_e32 v97, v0
	v_mov_b32_e32 v98, v0
	v_mov_b32_e32 v99, v0
	v_mov_b32_e32 v100, v0
	v_mov_b32_e32 v101, v0
	v_mov_b32_e32 v102, v0
	v_mov_b32_e32 v103, v0
	v_mov_b32_e32 v120, v0
	v_mov_b32_e32 v121, v0
	v_mov_b32_e32 v122, v0
	v_mov_b32_e32 v123, v0
	v_mov_b32_e32 v124, v0
	v_mov_b32_e32 v125, v0
	v_mov_b32_e32 v126, v0
	v_mov_b32_e32 v127, v0
	v_mov_b32_e32 v72, v0
	v_mov_b32_e32 v73, v0
	v_mov_b32_e32 v74, v0
	v_mov_b32_e32 v75, v0
	v_mov_b32_e32 v76, v0
	v_mov_b32_e32 v77, v0
	v_mov_b32_e32 v78, v0
	v_mov_b32_e32 v79, v0
	v_mov_b32_e32 v88, v0
	v_mov_b32_e32 v89, v0
	v_mov_b32_e32 v90, v0
	v_mov_b32_e32 v91, v0
	v_mov_b32_e32 v92, v0
	v_mov_b32_e32 v93, v0
	v_mov_b32_e32 v94, v0
	v_mov_b32_e32 v95, v0
	v_mov_b32_e32 v104, v0
	v_mov_b32_e32 v105, v0
	v_mov_b32_e32 v106, v0
	v_mov_b32_e32 v107, v0
	v_mov_b32_e32 v108, v0
	v_mov_b32_e32 v109, v0
	v_mov_b32_e32 v110, v0
	v_mov_b32_e32 v111, v0
	v_mov_b32_e32 v136, v0
	v_mov_b32_e32 v137, v0
	v_mov_b32_e32 v138, v0
	v_mov_b32_e32 v139, v0
	v_mov_b32_e32 v140, v0
	v_mov_b32_e32 v141, v0
	v_mov_b32_e32 v142, v0
	v_mov_b32_e32 v143, v0
	.p2align 6

;     __device__ __forceinline__ bool next(int i, pg8::Unit& u) const { if (c < 128 || i >= 2) return false; const int idx = (c - 128) * 2 + i; u.pm = idx >> 2; u.pn = idx & 3; return true; }
; template <class Epi, class Sched, bool ALIGN_EPI = false, bool SP2 = false, bool F16 = false>
; __device__ __forceinline__ void gemm_phase(PG8_LAS unsigned char* lds, const Gemm g, const Sched& S, const Epi& E, const int wid_in) {
;     ...
;         const bool has_next = S.next(ui + 1, nxt);
;         const char* nA = has_next ? (const char*)g.A + (size_t)nxt.pm * tstep : cA; const char* nB = has_next ? (const char*)g.Bt + (size_t)nxt.pn * tstep : cB;
;         for (int t = 0; t < nt; t += 2) {
;             const bool last = (t == nt - 2);
;             const char* a1 = cA + (size_t)(t + 1) * kstep;
;             const char* a2 = last ? nA : cA + (size_t)(t + 2) * kstep; const char* b2 = last ? nB : cB + (size_t)(t + 2) * kstep;
;             const char* a3 = a2 + kstep; const char* b3 = b2 + kstep;
;     ...
; #pragma unroll
;         for (int a = 0; a < 2; ++a)
; #pragma unroll
;             for (int b = 0; b < 2; ++b)
; #pragma unroll
;                 for (int m = 0; m < 4; ++m)
; #pragma unroll
;                     for (int n = 0; n < 2; ++n) acc[a][b][m][n] = (f32x4){0.f, 0.f, 0.f, 0.f};
;         cur = nxt; cA = nA; cB = nB; ++ui;
.LBB0_1547:
	s_ashr_i32 s45, s44, 31
	s_lshl_b64 s[40:41], s[44:45], 19
	s_add_u32 s46, s62, s40
	s_addc_u32 s47, s63, s41
	s_and_b64 s[40:41], s[10:11], exec
	s_cselect_b32 s13, s47, s51
	s_cselect_b32 s31, s46, s50
	s_ashr_i32 s37, s36, 31
	s_lshl_b64 s[40:41], s[36:37], 19
	s_add_u32 s48, s64, s40
	s_addc_u32 s49, s65, s41
	s_and_b64 s[40:41], s[10:11], exec
	s_cselect_b32 s37, s49, s53
	s_cselect_b32 s40, s48, s52
	s_add_u32 s50, s50, 0x40080
	s_addc_u32 s51, s51, 0
	s_add_u32 s41, s52, 0x100
	v_mov_b32_e32 v0, 0
	s_addc_u32 s42, s53, 0
	s_mov_b32 s43, -2
	s_waitcnt lgkmcnt(0)
	v_mov_b32_e32 v1, v0
	v_mov_b32_e32 v2, v0
	v_mov_b32_e32 v3, v0
	v_mov_b32_e32 v4, v0
	v_mov_b32_e32 v5, v0
	v_mov_b32_e32 v6, v0
	v_mov_b32_e32 v7, v0
	v_mov_b32_e32 v16, v0
	v_mov_b32_e32 v17, v0
	v_mov_b32_e32 v18, v0
	v_mov_b32_e32 v19, v0
	v_mov_b32_e32 v20, v0
	v_mov_b32_e32 v21, v0
	v_mov_b32_e32 v22, v0
	v_mov_b32_e32 v23, v0
	v_mov_b32_e32 v32, v0
	v_mov_b32_e32 v33, v0
	v_mov_b32_e32 v34, v0
	v_mov_b32_e32 v35, v0
	v_mov_b32_e32 v36, v0
	v_mov_b32_e32 v37, v0
	v_mov_b32_e32 v38, v0
	v_mov_b32_e32 v39, v0
	v_mov_b32_e32 v48, v0
	v_mov_b32_e32 v49, v0
	v_mov_b32_e32 v50, v0
	v_mov_b32_e32 v51, v0
	v_mov_b32_e32 v52, v0
	v_mov_b32_e32 v53, v0
	v_mov_b32_e32 v54, v0
	v_mov_b32_e32 v55, v0
	v_mov_b32_e32 v8, v0
	v_mov_b32_e32 v9, v0
	v_mov_b32_e32 v10, v0
	v_mov_b32_e32 v11, v0
	v_mov_b32_e32 v12, v0
	v_mov_b32_e32 v13, v0
	v_mov_b32_e32 v14, v0
	v_mov_b32_e32 v15, v0
	v_mov_b32_e32 v24, v0
	v_mov_b32_e32 v25, v0
	v_mov_b32_e32 v26, v0
	v_mov_b32_e32 v27, v0
	v_mov_b32_e32 v28, v0
	v_mov_b32_e32 v29, v0
	v_mov_b32_e32 v30, v0
	v_mov_b32_e32 v31, v0
	v_mov_b32_e32 v40, v0
	v_mov_b32_e32 v41, v0
	v_mov_b32_e32 v42, v0
	v_mov_b32_e32 v43, v0
	v_mov_b32_e32 v44, v0
	v_mov_b32_e32 v45, v0
	v_mov_b32_e32 v46, v0
	v_mov_b32_e32 v47, v0
	v_mov_b32_e32 v56, v0
	v_mov_b32_e32 v57, v0
	v_mov_b32_e32 v58, v0
	v_mov_b32_e32 v59, v0
	v_mov_b32_e32 v60, v0
	v_mov_b32_e32 v61, v0
	v_mov_b32_e32 v62, v0
	v_mov_b32_e32 v63, v0
	v_mov_b32_e32 v64, v0
	v_mov_b32_e32 v65, v0
	v_mov_b32_e32 v66, v0
	v_mov_b32_e32 v67, v0
	v_mov_b32_e32 v68, v0
	v_mov_b32_e32 v69, v0
	v_mov_b32_e32 v70, v0
	v_mov_b32_e32 v71, v0
	v_mov_b32_e32 v80, v0
	v_mov_b32_e32 v81, v0
	v_mov_b32_e32 v82, v0
	v_mov_b32_e32 v83, v0
	v_mov_b32_e32 v84, v0
	v_mov_b32_e32 v85, v0
	v_mov_b32_e32 v86, v0
	v_mov_b32_e32 v87, v0
	v_mov_b32_e32 v96, v0
	v_mov_b32_e32 v97, v0
	v_mov_b32_e32 v98, v0
	v_mov_b32_e32 v99, v0
	v_mov_b32_e32 v100, v0
	v_mov_b32_e32 v101, v0
	v_mov_b32_e32 v102, v0
	v_mov_b32_e32 v103, v0
	v_mov_b32_e32 v112, v0
	v_mov_b32_e32 v113, v0
	v_mov_b32_e32 v114, v0
	v_mov_b32_e32 v115, v0
	v_mov_b32_e32 v116, v0
	v_mov_b32_e32 v117, v0
	v_mov_b32_e32 v118, v0
	v_mov_b32_e32 v119, v0
	v_mov_b32_e32 v72, v0
	v_mov_b32_e32 v73, v0
	v_mov_b32_e32 v74, v0
	v_mov_b32_e32 v75, v0
	v_mov_b32_e32 v76, v0
	v_mov_b32_e32 v77, v0
	v_mov_b32_e32 v78, v0
	v_mov_b32_e32 v79, v0
	v_mov_b32_e32 v88, v0
	v_mov_b32_e32 v89, v0
	v_mov_b32_e32 v90, v0
	v_mov_b32_e32 v91, v0
	v_mov_b32_e32 v92, v0
	v_mov_b32_e32 v93, v0
	v_mov_b32_e32 v94, v0
	v_mov_b32_e32 v95, v0
	v_mov_b32_e32 v104, v0
	v_mov_b32_e32 v105, v0
	v_mov_b32_e32 v106, v0
	v_mov_b32_e32 v107, v0
	v_mov_b32_e32 v108, v0
	v_mov_b32_e32 v109, v0
	v_mov_b32_e32 v110, v0
	v_mov_b32_e32 v111, v0
	v_mov_b32_e32 v120, v0
	v_mov_b32_e32 v121, v0
	v_mov_b32_e32 v122, v0
	v_mov_b32_e32 v123, v0
	v_mov_b32_e32 v124, v0
	v_mov_b32_e32 v125, v0
	v_mov_b32_e32 v126, v0
	v_mov_b32_e32 v127, v0
	.p2align 6

;     __device__ __forceinline__ bool next(int i, pg8::Unit& u) const { if (c < 128 || i >= 2) return false; const int idx = (c - 128) * 2 + i; u.pm = idx >> 2; u.pn = idx & 3; return true; }
; template <class Epi, class Sched, bool ALIGN_EPI = false, bool SP2 = false, bool F16 = false>
; __device__ __forceinline__ void gemm_phase(PG8_LAS unsigned char* lds, const Gemm g, const Sched& S, const Epi& E, const int wid_in) {
;     ...
;         const bool has_next = S.next(ui + 1, nxt);
;         const char* nA = has_next ? (const char*)g.A + (size_t)nxt.pm * tstep : cA; const char* nB = has_next ? (const char*)g.Bt + (size_t)nxt.pn * tstep : cB;
;         for (int t = 0; t < nt; t += 2) {
;             const bool last = (t == nt - 2);
;             const char* a1 = cA + (size_t)(t + 1) * kstep;
;             const char* a2 = last ? nA : cA + (size_t)(t + 2) * kstep; const char* b2 = last ? nB : cB + (size_t)(t + 2) * kstep;
;             const char* a3 = a2 + kstep; const char* b3 = b2 + kstep;
;     ...
; #pragma unroll
;         for (int a = 0; a < 2; ++a)
; #pragma unroll
;             for (int b = 0; b < 2; ++b)
; #pragma unroll
;                 for (int m = 0; m < 4; ++m)
; #pragma unroll
;                     for (int n = 0; n < 2; ++n) acc[a][b][m][n] = (f32x4){0.f, 0.f, 0.f, 0.f};
;         cur = nxt; cA = nA; cB = nB; ++ui;
.LBB0_1831:
	s_ashr_i32 s35, s34, 31
	s_lshl_b64 s[36:37], s[34:35], 19
	s_add_u32 s36, s15, s36
	s_addc_u32 s37, s19, s37
	s_and_b64 s[42:43], s[10:11], exec
	s_cselect_b32 s35, s37, s49
	s_cselect_b32 s42, s36, s48
	s_ashr_i32 s31, s30, 31
	s_lshl_b64 s[44:45], s[30:31], 19
	s_add_u32 s44, s21, s44
	s_addc_u32 s45, s40, s45
	s_and_b64 s[52:53], s[10:11], exec
	s_cselect_b32 s31, s45, s51
	s_cselect_b32 s43, s44, s50
	s_add_u32 s48, s48, 0x40080
	s_addc_u32 s49, s49, 0
	s_add_u32 s47, s50, 0x100
	v_mov_b32_e32 v0, 0
	s_addc_u32 s60, s51, 0
	s_mov_b32 s61, -2
	v_mov_b32_e32 v1, v0
	v_mov_b32_e32 v2, v0
	v_mov_b32_e32 v3, v0
	v_mov_b32_e32 v4, v0
	v_mov_b32_e32 v5, v0
	v_mov_b32_e32 v6, v0
	v_mov_b32_e32 v7, v0
	v_mov_b32_e32 v16, v0
	v_mov_b32_e32 v17, v0
	v_mov_b32_e32 v18, v0
	v_mov_b32_e32 v19, v0
	v_mov_b32_e32 v20, v0
	v_mov_b32_e32 v21, v0
	v_mov_b32_e32 v22, v0
	v_mov_b32_e32 v23, v0
	v_mov_b32_e32 v32, v0
	v_mov_b32_e32 v33, v0
	v_mov_b32_e32 v34, v0
	v_mov_b32_e32 v35, v0
	v_mov_b32_e32 v36, v0
	v_mov_b32_e32 v37, v0
	v_mov_b32_e32 v38, v0
	v_mov_b32_e32 v39, v0
	v_mov_b32_e32 v48, v0
	v_mov_b32_e32 v49, v0
	v_mov_b32_e32 v50, v0
	v_mov_b32_e32 v51, v0
	v_mov_b32_e32 v52, v0
	v_mov_b32_e32 v53, v0
	v_mov_b32_e32 v54, v0
	v_mov_b32_e32 v55, v0
	v_mov_b32_e32 v8, v0
	v_mov_b32_e32 v9, v0
	v_mov_b32_e32 v10, v0
	v_mov_b32_e32 v11, v0
	v_mov_b32_e32 v12, v0
	v_mov_b32_e32 v13, v0
	v_mov_b32_e32 v14, v0
	v_mov_b32_e32 v15, v0
	v_mov_b32_e32 v24, v0
	v_mov_b32_e32 v25, v0
	v_mov_b32_e32 v26, v0
	v_mov_b32_e32 v27, v0
	v_mov_b32_e32 v28, v0
	v_mov_b32_e32 v29, v0
	v_mov_b32_e32 v30, v0
	v_mov_b32_e32 v31, v0
	v_mov_b32_e32 v40, v0
	v_mov_b32_e32 v41, v0
	v_mov_b32_e32 v42, v0
	v_mov_b32_e32 v43, v0
	v_mov_b32_e32 v44, v0
	v_mov_b32_e32 v45, v0
	v_mov_b32_e32 v46, v0
	v_mov_b32_e32 v47, v0
	v_mov_b32_e32 v56, v0
	v_mov_b32_e32 v57, v0
	v_mov_b32_e32 v58, v0
	v_mov_b32_e32 v59, v0
	v_mov_b32_e32 v60, v0
	v_mov_b32_e32 v61, v0
	v_mov_b32_e32 v62, v0
	v_mov_b32_e32 v63, v0
	v_mov_b32_e32 v64, v0
	v_mov_b32_e32 v65, v0
	v_mov_b32_e32 v66, v0
	v_mov_b32_e32 v67, v0
	v_mov_b32_e32 v68, v0
	v_mov_b32_e32 v69, v0
	v_mov_b32_e32 v70, v0
	v_mov_b32_e32 v71, v0
	v_mov_b32_e32 v80, v0
	v_mov_b32_e32 v81, v0
	v_mov_b32_e32 v82, v0
	v_mov_b32_e32 v83, v0
	v_mov_b32_e32 v84, v0
	v_mov_b32_e32 v85, v0
	v_mov_b32_e32 v86, v0
	v_mov_b32_e32 v87, v0
	v_mov_b32_e32 v96, v0
	v_mov_b32_e32 v97, v0
	v_mov_b32_e32 v98, v0
	v_mov_b32_e32 v99, v0
	v_mov_b32_e32 v100, v0
	v_mov_b32_e32 v101, v0
	v_mov_b32_e32 v102, v0
	v_mov_b32_e32 v103, v0
	v_mov_b32_e32 v112, v0
	v_mov_b32_e32 v113, v0
	v_mov_b32_e32 v114, v0
	v_mov_b32_e32 v115, v0
	v_mov_b32_e32 v116, v0
	v_mov_b32_e32 v117, v0
	v_mov_b32_e32 v118, v0
	v_mov_b32_e32 v119, v0
	v_mov_b32_e32 v72, v0
	v_mov_b32_e32 v73, v0
	v_mov_b32_e32 v74, v0
	v_mov_b32_e32 v75, v0
	v_mov_b32_e32 v76, v0
	v_mov_b32_e32 v77, v0
	v_mov_b32_e32 v78, v0
	v_mov_b32_e32 v79, v0
	v_mov_b32_e32 v88, v0
	v_mov_b32_e32 v89, v0
	v_mov_b32_e32 v90, v0
	v_mov_b32_e32 v91, v0
	v_mov_b32_e32 v92, v0
	v_mov_b32_e32 v93, v0
	v_mov_b32_e32 v94, v0
	v_mov_b32_e32 v95, v0
	v_mov_b32_e32 v104, v0
	v_mov_b32_e32 v105, v0
	v_mov_b32_e32 v106, v0
	v_mov_b32_e32 v107, v0
	v_mov_b32_e32 v108, v0
	v_mov_b32_e32 v109, v0
	v_mov_b32_e32 v110, v0
	v_mov_b32_e32 v111, v0
	v_mov_b32_e32 v120, v0
	v_mov_b32_e32 v121, v0
	v_mov_b32_e32 v122, v0
	v_mov_b32_e32 v123, v0
	v_mov_b32_e32 v124, v0
	v_mov_b32_e32 v125, v0
	v_mov_b32_e32 v126, v0
	v_mov_b32_e32 v127, v0
	.p2align 6

;     __device__ __forceinline__ bool next(int i, pg8::Unit& u) const { if (c < 128 || i >= 2) return false; const int idx = (c - 128) * 2 + i; u.pm = idx >> 2; u.pn = idx & 3; return true; }
; template <class Epi, class Sched, bool ALIGN_EPI = false, bool SP2 = false, bool F16 = false>
; __device__ __forceinline__ void gemm_phase(PG8_LAS unsigned char* lds, const Gemm g, const Sched& S, const Epi& E, const int wid_in) {
;     ...
;         const bool has_next = S.next(ui + 1, nxt);
;         const char* nA = has_next ? (const char*)g.A + (size_t)nxt.pm * tstep : cA; const char* nB = has_next ? (const char*)g.Bt + (size_t)nxt.pn * tstep : cB;
;         for (int t = 0; t < nt; t += 2) {
;             const bool last = (t == nt - 2);
;             const char* a1 = cA + (size_t)(t + 1) * kstep;
;             const char* a2 = last ? nA : cA + (size_t)(t + 2) * kstep; const char* b2 = last ? nB : cB + (size_t)(t + 2) * kstep;
;             const char* a3 = a2 + kstep; const char* b3 = b2 + kstep;
;     ...
; #pragma unroll
;         for (int a = 0; a < 2; ++a)
; #pragma unroll
;             for (int b = 0; b < 2; ++b)
; #pragma unroll
;                 for (int m = 0; m < 4; ++m)
; #pragma unroll
;                     for (int n = 0; n < 2; ++n) acc[a][b][m][n] = (f32x4){0.f, 0.f, 0.f, 0.f};
;         cur = nxt; cA = nA; cB = nB; ++ui;
.LBB0_1908:
	s_ashr_i32 s29, s28, 31
	s_lshl_b64 s[30:31], s[28:29], 19
	s_add_u32 s30, s21, s30
	s_addc_u32 s31, s40, s31
	s_and_b64 s[34:35], s[10:11], exec
	s_cselect_b32 s29, s31, s47
	s_cselect_b32 s42, s30, s46
	s_ashr_i32 s27, s26, 31
	s_lshl_b64 s[34:35], s[26:27], 19
	s_add_u32 s34, s41, s34
	s_addc_u32 s35, s52, s35
	s_and_b64 s[50:51], s[10:11], exec
	s_cselect_b32 s27, s35, s49
	s_cselect_b32 s43, s34, s48
	s_add_u32 s46, s46, 0x40080
	s_addc_u32 s47, s47, 0
	s_add_u32 s45, s48, 0x100
	v_mov_b32_e32 v8, 0
	s_addc_u32 s63, s49, 0
	s_mov_b32 s64, -2
	v_mov_b32_e32 v9, v8
	v_mov_b32_e32 v10, v8
	v_mov_b32_e32 v11, v8
	v_mov_b32_e32 v12, v8
	v_mov_b32_e32 v13, v8
	v_mov_b32_e32 v14, v8
	v_mov_b32_e32 v15, v8
	v_mov_b32_e32 v24, v8
	v_mov_b32_e32 v25, v8
	v_mov_b32_e32 v26, v8
	v_mov_b32_e32 v27, v8
	v_mov_b32_e32 v28, v8
	v_mov_b32_e32 v29, v8
	v_mov_b32_e32 v30, v8
	v_mov_b32_e32 v31, v8
	v_mov_b32_e32 v40, v8
	v_mov_b32_e32 v41, v8
	v_mov_b32_e32 v42, v8
	v_mov_b32_e32 v43, v8
	v_mov_b32_e32 v44, v8
	v_mov_b32_e32 v45, v8
	v_mov_b32_e32 v46, v8
	v_mov_b32_e32 v47, v8
	v_mov_b32_e32 v56, v8
	v_mov_b32_e32 v57, v8
	v_mov_b32_e32 v58, v8
	v_mov_b32_e32 v59, v8
	v_mov_b32_e32 v60, v8
	v_mov_b32_e32 v61, v8
	v_mov_b32_e32 v62, v8
	v_mov_b32_e32 v63, v8
	v_mov_b32_e32 v16, v8
	v_mov_b32_e32 v17, v8
	v_mov_b32_e32 v18, v8
	v_mov_b32_e32 v19, v8
	v_mov_b32_e32 v20, v8
	v_mov_b32_e32 v21, v8
	v_mov_b32_e32 v22, v8
	v_mov_b32_e32 v23, v8
	v_mov_b32_e32 v32, v8
	v_mov_b32_e32 v33, v8
	v_mov_b32_e32 v34, v8
	v_mov_b32_e32 v35, v8
	v_mov_b32_e32 v36, v8
	v_mov_b32_e32 v37, v8
	v_mov_b32_e32 v38, v8
	v_mov_b32_e32 v39, v8
	v_mov_b32_e32 v48, v8
	v_mov_b32_e32 v49, v8
	v_mov_b32_e32 v50, v8
	v_mov_b32_e32 v51, v8
	v_mov_b32_e32 v52, v8
	v_mov_b32_e32 v53, v8
	v_mov_b32_e32 v54, v8
	v_mov_b32_e32 v55, v8
	v_mov_b32_e32 v64, v8
	v_mov_b32_e32 v65, v8
	v_mov_b32_e32 v66, v8
	v_mov_b32_e32 v67, v8
	v_mov_b32_e32 v68, v8
	v_mov_b32_e32 v69, v8
	v_mov_b32_e32 v70, v8
	v_mov_b32_e32 v71, v8
	v_mov_b32_e32 v72, v8
	v_mov_b32_e32 v73, v8
	v_mov_b32_e32 v74, v8
	v_mov_b32_e32 v75, v8
	v_mov_b32_e32 v76, v8
	v_mov_b32_e32 v77, v8
	v_mov_b32_e32 v78, v8
	v_mov_b32_e32 v79, v8
	v_mov_b32_e32 v88, v8
	v_mov_b32_e32 v89, v8
	v_mov_b32_e32 v90, v8
	v_mov_b32_e32 v91, v8
	v_mov_b32_e32 v92, v8
	v_mov_b32_e32 v93, v8
	v_mov_b32_e32 v94, v8
	v_mov_b32_e32 v95, v8
	v_mov_b32_e32 v104, v8
	v_mov_b32_e32 v105, v8
	v_mov_b32_e32 v106, v8
	v_mov_b32_e32 v107, v8
	v_mov_b32_e32 v108, v8
	v_mov_b32_e32 v109, v8
	v_mov_b32_e32 v110, v8
	v_mov_b32_e32 v111, v8
	v_mov_b32_e32 v120, v8
	v_mov_b32_e32 v121, v8
	v_mov_b32_e32 v122, v8
	v_mov_b32_e32 v123, v8
	v_mov_b32_e32 v124, v8
	v_mov_b32_e32 v125, v8
	v_mov_b32_e32 v126, v8
	v_mov_b32_e32 v127, v8
	v_mov_b32_e32 v80, v8
	v_mov_b32_e32 v81, v8
	v_mov_b32_e32 v82, v8
	v_mov_b32_e32 v83, v8
	v_mov_b32_e32 v84, v8
	v_mov_b32_e32 v85, v8
	v_mov_b32_e32 v86, v8
	v_mov_b32_e32 v87, v8
	v_mov_b32_e32 v96, v8
	v_mov_b32_e32 v97, v8
	v_mov_b32_e32 v98, v8
	v_mov_b32_e32 v99, v8
	v_mov_b32_e32 v100, v8
	v_mov_b32_e32 v101, v8
	v_mov_b32_e32 v102, v8
	v_mov_b32_e32 v103, v8
	v_mov_b32_e32 v112, v8
	v_mov_b32_e32 v113, v8
	v_mov_b32_e32 v114, v8
	v_mov_b32_e32 v115, v8
	v_mov_b32_e32 v116, v8
	v_mov_b32_e32 v117, v8
	v_mov_b32_e32 v118, v8
	v_mov_b32_e32 v119, v8
	v_mov_b32_e32 v128, v8
	v_mov_b32_e32 v129, v8
	v_mov_b32_e32 v130, v8
	v_mov_b32_e32 v131, v8
	v_mov_b32_e32 v132, v8
	v_mov_b32_e32 v133, v8
	v_mov_b32_e32 v134, v8
	v_mov_b32_e32 v135, v8
	.p2align 6

; template <class Epi, class Sched, bool ALIGN_EPI = false, bool SP2 = false, bool F16 = false>
; __device__ __forceinline__ void gemm_phase(PG8_LAS unsigned char* lds, const Gemm g, const Sched& S, const Epi& E, const int wid_in) {
;     ...
;             const char* a1 = cA + (size_t)(t + 1) * kstep;
;             const char* a2 = last ? nA : cA + (size_t)(t + 2) * kstep; const char* b2 = last ? nB : cB + (size_t)(t + 2) * kstep;
;             const char* a3 = a2 + kstep; const char* b3 = b2 + kstep;
;     ...
; #pragma unroll
;         for (int a = 0; a < 2; ++a)
; #pragma unroll
;             for (int b = 0; b < 2; ++b)
; #pragma unroll
;                 for (int m = 0; m < 4; ++m)
; #pragma unroll
;                     for (int n = 0; n < 2; ++n) acc[a][b][m][n] = (f32x4){0.f, 0.f, 0.f, 0.f};
;         cur = nxt; cA = nA; cB = nB; ++ui;
.LBB0_2039:
	s_add_u32 s43, s44, 0x100
	v_mov_b32_e32 v0, 0
	s_addc_u32 s58, s45, 0
	s_mov_b32 s59, -2
	v_mov_b32_e32 v1, v0
	v_mov_b32_e32 v2, v0
	v_mov_b32_e32 v3, v0
	v_mov_b32_e32 v4, v0
	v_mov_b32_e32 v5, v0
	v_mov_b32_e32 v6, v0
	v_mov_b32_e32 v7, v0
	v_mov_b32_e32 v16, v0
	v_mov_b32_e32 v17, v0
	v_mov_b32_e32 v18, v0
	v_mov_b32_e32 v19, v0
	v_mov_b32_e32 v20, v0
	v_mov_b32_e32 v21, v0
	v_mov_b32_e32 v22, v0
	v_mov_b32_e32 v23, v0
	v_mov_b32_e32 v32, v0
	v_mov_b32_e32 v33, v0
	v_mov_b32_e32 v34, v0
	v_mov_b32_e32 v35, v0
	v_mov_b32_e32 v36, v0
	v_mov_b32_e32 v37, v0
	v_mov_b32_e32 v38, v0
	v_mov_b32_e32 v39, v0
	v_mov_b32_e32 v48, v0
	v_mov_b32_e32 v49, v0
	v_mov_b32_e32 v50, v0
	v_mov_b32_e32 v51, v0
	v_mov_b32_e32 v52, v0
	v_mov_b32_e32 v53, v0
	v_mov_b32_e32 v54, v0
	v_mov_b32_e32 v55, v0
	v_mov_b32_e32 v8, v0
	v_mov_b32_e32 v9, v0
	v_mov_b32_e32 v10, v0
	v_mov_b32_e32 v11, v0
	v_mov_b32_e32 v12, v0
	v_mov_b32_e32 v13, v0
	v_mov_b32_e32 v14, v0
	v_mov_b32_e32 v15, v0
	v_mov_b32_e32 v24, v0
	v_mov_b32_e32 v25, v0
	v_mov_b32_e32 v26, v0
	v_mov_b32_e32 v27, v0
	v_mov_b32_e32 v28, v0
	v_mov_b32_e32 v29, v0
	v_mov_b32_e32 v30, v0
	v_mov_b32_e32 v31, v0
	v_mov_b32_e32 v40, v0
	v_mov_b32_e32 v41, v0
	v_mov_b32_e32 v42, v0
	v_mov_b32_e32 v43, v0
	v_mov_b32_e32 v44, v0
	v_mov_b32_e32 v45, v0
	v_mov_b32_e32 v46, v0
	v_mov_b32_e32 v47, v0
	v_mov_b32_e32 v56, v0
	v_mov_b32_e32 v57, v0
	v_mov_b32_e32 v58, v0
	v_mov_b32_e32 v59, v0
	v_mov_b32_e32 v60, v0
	v_mov_b32_e32 v61, v0
	v_mov_b32_e32 v62, v0
	v_mov_b32_e32 v63, v0
	v_mov_b32_e32 v64, v0
	v_mov_b32_e32 v65, v0
	v_mov_b32_e32 v66, v0
	v_mov_b32_e32 v67, v0
	v_mov_b32_e32 v68, v0
	v_mov_b32_e32 v69, v0
	v_mov_b32_e32 v70, v0
	v_mov_b32_e32 v71, v0
	v_mov_b32_e32 v80, v0
	v_mov_b32_e32 v81, v0
	v_mov_b32_e32 v82, v0
	v_mov_b32_e32 v83, v0
	v_mov_b32_e32 v84, v0
	v_mov_b32_e32 v85, v0
	v_mov_b32_e32 v86, v0
	v_mov_b32_e32 v87, v0
	v_mov_b32_e32 v96, v0
	v_mov_b32_e32 v97, v0
	v_mov_b32_e32 v98, v0
	v_mov_b32_e32 v99, v0
	v_mov_b32_e32 v100, v0
	v_mov_b32_e32 v101, v0
	v_mov_b32_e32 v102, v0
	v_mov_b32_e32 v103, v0
	v_mov_b32_e32 v112, v0
	v_mov_b32_e32 v113, v0
	v_mov_b32_e32 v114, v0
	v_mov_b32_e32 v115, v0
	v_mov_b32_e32 v116, v0
	v_mov_b32_e32 v117, v0
	v_mov_b32_e32 v118, v0
	v_mov_b32_e32 v119, v0
	v_mov_b32_e32 v72, v0
	v_mov_b32_e32 v73, v0
	v_mov_b32_e32 v74, v0
	v_mov_b32_e32 v75, v0
	v_mov_b32_e32 v76, v0
	v_mov_b32_e32 v77, v0
	v_mov_b32_e32 v78, v0
	v_mov_b32_e32 v79, v0
	v_mov_b32_e32 v88, v0
	v_mov_b32_e32 v89, v0
	v_mov_b32_e32 v90, v0
	v_mov_b32_e32 v91, v0
	v_mov_b32_e32 v92, v0
	v_mov_b32_e32 v93, v0
	v_mov_b32_e32 v94, v0
	v_mov_b32_e32 v95, v0
	v_mov_b32_e32 v104, v0
	v_mov_b32_e32 v105, v0
	v_mov_b32_e32 v106, v0
	v_mov_b32_e32 v107, v0
	v_mov_b32_e32 v108, v0
	v_mov_b32_e32 v109, v0
	v_mov_b32_e32 v110, v0
	v_mov_b32_e32 v111, v0
	v_mov_b32_e32 v120, v0
	v_mov_b32_e32 v121, v0
	v_mov_b32_e32 v122, v0
	v_mov_b32_e32 v123, v0
	v_mov_b32_e32 v124, v0
	v_mov_b32_e32 v125, v0
	v_mov_b32_e32 v126, v0
	v_mov_b32_e32 v127, v0
	.p2align 6

;     __device__ __forceinline__ bool next(int i, pg8::Unit& u) const { if (c < 128 || i >= 2) return false; const int idx = (c - 128) * 2 + i; u.pm = idx >> 2; u.pn = idx & 3; return true; }
; template <class Epi, class Sched, bool ALIGN_EPI = false, bool SP2 = false, bool F16 = false>
; __device__ __forceinline__ void gemm_phase(PG8_LAS unsigned char* lds, const Gemm g, const Sched& S, const Epi& E, const int wid_in) {
;     ...
;         const bool has_next = S.next(ui + 1, nxt);
;         const char* nA = has_next ? (const char*)g.A + (size_t)nxt.pm * tstep : cA; const char* nB = has_next ? (const char*)g.Bt + (size_t)nxt.pn * tstep : cB;
;         for (int t = 0; t < nt; t += 2) {
;             const bool last = (t == nt - 2);
;             const char* a1 = cA + (size_t)(t + 1) * kstep;
;             const char* a2 = last ? nA : cA + (size_t)(t + 2) * kstep; const char* b2 = last ? nB : cB + (size_t)(t + 2) * kstep;
;             const char* a3 = a2 + kstep; const char* b3 = b2 + kstep;
;     ...
; #pragma unroll
;         for (int a = 0; a < 2; ++a)
; #pragma unroll
;             for (int b = 0; b < 2; ++b)
; #pragma unroll
;                 for (int m = 0; m < 4; ++m)
; #pragma unroll
;                     for (int n = 0; n < 2; ++n) acc[a][b][m][n] = (f32x4){0.f, 0.f, 0.f, 0.f};
;         cur = nxt; cA = nA; cB = nB; ++ui;
.LBB0_2225:
	s_ashr_i32 s37, s36, 31
	s_lshl_b64 s[40:41], s[36:37], 19
	s_add_u32 s44, s59, s40
	s_addc_u32 s45, s60, s41
	s_and_b64 s[40:41], s[10:11], exec
	s_cselect_b32 s13, s45, s49
	s_cselect_b32 s23, s44, s48
	s_ashr_i32 s35, s34, 31
	s_lshl_b64 s[40:41], s[34:35], 19
	s_add_u32 s46, s61, s40
	s_addc_u32 s47, s62, s41
	s_and_b64 s[40:41], s[10:11], exec
	s_cselect_b32 s35, s47, s51
	s_cselect_b32 s37, s46, s50
	s_add_u32 s48, s48, 0x40080
	s_addc_u32 s49, s49, 0
	s_add_u32 s40, s50, 0x100
	v_mov_b32_e32 v0, 0
	s_addc_u32 s41, s51, 0
	s_mov_b32 s42, -2
	s_waitcnt lgkmcnt(0)
	v_mov_b32_e32 v1, v0
	v_mov_b32_e32 v2, v0
	v_mov_b32_e32 v3, v0
	v_mov_b32_e32 v4, v0
	v_mov_b32_e32 v5, v0
	v_mov_b32_e32 v6, v0
	v_mov_b32_e32 v7, v0
	v_mov_b32_e32 v16, v0
	v_mov_b32_e32 v17, v0
	v_mov_b32_e32 v18, v0
	v_mov_b32_e32 v19, v0
	v_mov_b32_e32 v20, v0
	v_mov_b32_e32 v21, v0
	v_mov_b32_e32 v22, v0
	v_mov_b32_e32 v23, v0
	v_mov_b32_e32 v32, v0
	v_mov_b32_e32 v33, v0
	v_mov_b32_e32 v34, v0
	v_mov_b32_e32 v35, v0
	v_mov_b32_e32 v36, v0
	v_mov_b32_e32 v37, v0
	v_mov_b32_e32 v38, v0
	v_mov_b32_e32 v39, v0
	v_mov_b32_e32 v48, v0
	v_mov_b32_e32 v49, v0
	v_mov_b32_e32 v50, v0
	v_mov_b32_e32 v51, v0
	v_mov_b32_e32 v52, v0
	v_mov_b32_e32 v53, v0
	v_mov_b32_e32 v54, v0
	v_mov_b32_e32 v55, v0
	v_mov_b32_e32 v8, v0
	v_mov_b32_e32 v9, v0
	v_mov_b32_e32 v10, v0
	v_mov_b32_e32 v11, v0
	v_mov_b32_e32 v12, v0
	v_mov_b32_e32 v13, v0
	v_mov_b32_e32 v14, v0
	v_mov_b32_e32 v15, v0
	v_mov_b32_e32 v24, v0
	v_mov_b32_e32 v25, v0
	v_mov_b32_e32 v26, v0
	v_mov_b32_e32 v27, v0
	v_mov_b32_e32 v28, v0
	v_mov_b32_e32 v29, v0
	v_mov_b32_e32 v30, v0
	v_mov_b32_e32 v31, v0
	v_mov_b32_e32 v40, v0
	v_mov_b32_e32 v41, v0
	v_mov_b32_e32 v42, v0
	v_mov_b32_e32 v43, v0
	v_mov_b32_e32 v44, v0
	v_mov_b32_e32 v45, v0
	v_mov_b32_e32 v46, v0
	v_mov_b32_e32 v47, v0
	v_mov_b32_e32 v56, v0
	v_mov_b32_e32 v57, v0
	v_mov_b32_e32 v58, v0
	v_mov_b32_e32 v59, v0
	v_mov_b32_e32 v60, v0
	v_mov_b32_e32 v61, v0
	v_mov_b32_e32 v62, v0
	v_mov_b32_e32 v63, v0
	v_mov_b32_e32 v64, v0
	v_mov_b32_e32 v65, v0
	v_mov_b32_e32 v66, v0
	v_mov_b32_e32 v67, v0
	v_mov_b32_e32 v68, v0
	v_mov_b32_e32 v69, v0
	v_mov_b32_e32 v70, v0
	v_mov_b32_e32 v71, v0
	v_mov_b32_e32 v80, v0
	v_mov_b32_e32 v81, v0
	v_mov_b32_e32 v82, v0
	v_mov_b32_e32 v83, v0
	v_mov_b32_e32 v84, v0
	v_mov_b32_e32 v85, v0
	v_mov_b32_e32 v86, v0
	v_mov_b32_e32 v87, v0
	v_mov_b32_e32 v96, v0
	v_mov_b32_e32 v97, v0
	v_mov_b32_e32 v98, v0
	v_mov_b32_e32 v99, v0
	v_mov_b32_e32 v100, v0
	v_mov_b32_e32 v101, v0
	v_mov_b32_e32 v102, v0
	v_mov_b32_e32 v103, v0
	v_mov_b32_e32 v112, v0
	v_mov_b32_e32 v113, v0
	v_mov_b32_e32 v114, v0
	v_mov_b32_e32 v115, v0
	v_mov_b32_e32 v116, v0
	v_mov_b32_e32 v117, v0
	v_mov_b32_e32 v118, v0
	v_mov_b32_e32 v119, v0
	v_mov_b32_e32 v72, v0
	v_mov_b32_e32 v73, v0
	v_mov_b32_e32 v74, v0
	v_mov_b32_e32 v75, v0
	v_mov_b32_e32 v76, v0
	v_mov_b32_e32 v77, v0
	v_mov_b32_e32 v78, v0
	v_mov_b32_e32 v79, v0
	v_mov_b32_e32 v88, v0
	v_mov_b32_e32 v89, v0
	v_mov_b32_e32 v90, v0
	v_mov_b32_e32 v91, v0
	v_mov_b32_e32 v92, v0
	v_mov_b32_e32 v93, v0
	v_mov_b32_e32 v94, v0
	v_mov_b32_e32 v95, v0
	v_mov_b32_e32 v104, v0
	v_mov_b32_e32 v105, v0
	v_mov_b32_e32 v106, v0
	v_mov_b32_e32 v107, v0
	v_mov_b32_e32 v108, v0
	v_mov_b32_e32 v109, v0
	v_mov_b32_e32 v110, v0
	v_mov_b32_e32 v111, v0
	v_mov_b32_e32 v120, v0
	v_mov_b32_e32 v121, v0
	v_mov_b32_e32 v122, v0
	v_mov_b32_e32 v123, v0
	v_mov_b32_e32 v124, v0
	v_mov_b32_e32 v125, v0
	v_mov_b32_e32 v126, v0
	v_mov_b32_e32 v127, v0
	.p2align 6

;     __device__ __forceinline__ bool next(int i, pg8::Unit& u) const { if (c < 128 || i >= 2) return false; const int idx = (c - 128) * 2 + i; u.pm = idx >> 2; u.pn = idx & 3; return true; }
; template <class Epi, class Sched, bool ALIGN_EPI = false, bool SP2 = false, bool F16 = false>
; __device__ __forceinline__ void gemm_phase(PG8_LAS unsigned char* lds, const Gemm g, const Sched& S, const Epi& E, const int wid_in) {
;     ...
;         const bool has_next = S.next(ui + 1, nxt);
;         const char* nA = has_next ? (const char*)g.A + (size_t)nxt.pm * tstep : cA; const char* nB = has_next ? (const char*)g.Bt + (size_t)nxt.pn * tstep : cB;
;         for (int t = 0; t < nt; t += 2) {
;             const bool last = (t == nt - 2);
;             const char* a1 = cA + (size_t)(t + 1) * kstep;
;             const char* a2 = last ? nA : cA + (size_t)(t + 2) * kstep; const char* b2 = last ? nB : cB + (size_t)(t + 2) * kstep;
;             const char* a3 = a2 + kstep; const char* b3 = b2 + kstep;
;     ...
; #pragma unroll
;         for (int a = 0; a < 2; ++a)
; #pragma unroll
;             for (int b = 0; b < 2; ++b)
; #pragma unroll
;                 for (int m = 0; m < 4; ++m)
; #pragma unroll
;                     for (int n = 0; n < 2; ++n) acc[a][b][m][n] = (f32x4){0.f, 0.f, 0.f, 0.f};
;         cur = nxt; cA = nA; cB = nB; ++ui;
.LBB0_2488:
	s_ashr_i32 s29, s28, 31
	s_lshl_b64 s[30:31], s[28:29], 19
	s_add_u32 s30, s15, s30
	s_addc_u32 s31, s40, s31
	s_and_b64 s[34:35], s[10:11], exec
	s_cselect_b32 s29, s31, s43
	s_cselect_b32 s37, s30, s42
	s_ashr_i32 s27, s26, 31
	s_lshl_b64 s[34:35], s[26:27], 19
	s_add_u32 s34, s41, s34
	s_addc_u32 s35, s48, s35
	s_and_b64 s[46:47], s[10:11], exec
	s_cselect_b32 s27, s35, s45
	s_cselect_b32 s56, s34, s44
	s_add_u32 s42, s42, 0x40080
	s_addc_u32 s43, s43, 0
	s_add_u32 s57, s44, 0x100
	v_mov_b32_e32 v0, 0
	s_addc_u32 s58, s45, 0
	s_mov_b32 s59, -2
	v_mov_b32_e32 v1, v0
	v_mov_b32_e32 v2, v0
	v_mov_b32_e32 v3, v0
	v_mov_b32_e32 v4, v0
	v_mov_b32_e32 v5, v0
	v_mov_b32_e32 v6, v0
	v_mov_b32_e32 v7, v0
	v_mov_b32_e32 v16, v0
	v_mov_b32_e32 v17, v0
	v_mov_b32_e32 v18, v0
	v_mov_b32_e32 v19, v0
	v_mov_b32_e32 v20, v0
	v_mov_b32_e32 v21, v0
	v_mov_b32_e32 v22, v0
	v_mov_b32_e32 v23, v0
	v_mov_b32_e32 v32, v0
	v_mov_b32_e32 v33, v0
	v_mov_b32_e32 v34, v0
	v_mov_b32_e32 v35, v0
	v_mov_b32_e32 v36, v0
	v_mov_b32_e32 v37, v0
	v_mov_b32_e32 v38, v0
	v_mov_b32_e32 v39, v0
	v_mov_b32_e32 v48, v0
	v_mov_b32_e32 v49, v0
	v_mov_b32_e32 v50, v0
	v_mov_b32_e32 v51, v0
	v_mov_b32_e32 v52, v0
	v_mov_b32_e32 v53, v0
	v_mov_b32_e32 v54, v0
	v_mov_b32_e32 v55, v0
	v_mov_b32_e32 v8, v0
	v_mov_b32_e32 v9, v0
	v_mov_b32_e32 v10, v0
	v_mov_b32_e32 v11, v0
	v_mov_b32_e32 v12, v0
	v_mov_b32_e32 v13, v0
	v_mov_b32_e32 v14, v0
	v_mov_b32_e32 v15, v0
	v_mov_b32_e32 v24, v0
	v_mov_b32_e32 v25, v0
	v_mov_b32_e32 v26, v0
	v_mov_b32_e32 v27, v0
	v_mov_b32_e32 v28, v0
	v_mov_b32_e32 v29, v0
	v_mov_b32_e32 v30, v0
	v_mov_b32_e32 v31, v0
	v_mov_b32_e32 v40, v0
	v_mov_b32_e32 v41, v0
	v_mov_b32_e32 v42, v0
	v_mov_b32_e32 v43, v0
	v_mov_b32_e32 v44, v0
	v_mov_b32_e32 v45, v0
	v_mov_b32_e32 v46, v0
	v_mov_b32_e32 v47, v0
	v_mov_b32_e32 v56, v0
	v_mov_b32_e32 v57, v0
	v_mov_b32_e32 v58, v0
	v_mov_b32_e32 v59, v0
	v_mov_b32_e32 v60, v0
	v_mov_b32_e32 v61, v0
	v_mov_b32_e32 v62, v0
	v_mov_b32_e32 v63, v0
	v_mov_b32_e32 v64, v0
	v_mov_b32_e32 v65, v0
	v_mov_b32_e32 v66, v0
	v_mov_b32_e32 v67, v0
	v_mov_b32_e32 v68, v0
	v_mov_b32_e32 v69, v0
	v_mov_b32_e32 v70, v0
	v_mov_b32_e32 v71, v0
	v_mov_b32_e32 v80, v0
	v_mov_b32_e32 v81, v0
	v_mov_b32_e32 v82, v0
	v_mov_b32_e32 v83, v0
	v_mov_b32_e32 v84, v0
	v_mov_b32_e32 v85, v0
	v_mov_b32_e32 v86, v0
	v_mov_b32_e32 v87, v0
	v_mov_b32_e32 v96, v0
	v_mov_b32_e32 v97, v0
	v_mov_b32_e32 v98, v0
	v_mov_b32_e32 v99, v0
	v_mov_b32_e32 v100, v0
	v_mov_b32_e32 v101, v0
	v_mov_b32_e32 v102, v0
	v_mov_b32_e32 v103, v0
	v_mov_b32_e32 v112, v0
	v_mov_b32_e32 v113, v0
	v_mov_b32_e32 v114, v0
	v_mov_b32_e32 v115, v0
	v_mov_b32_e32 v116, v0
	v_mov_b32_e32 v117, v0
	v_mov_b32_e32 v118, v0
	v_mov_b32_e32 v119, v0
	v_mov_b32_e32 v72, v0
	v_mov_b32_e32 v73, v0
	v_mov_b32_e32 v74, v0
	v_mov_b32_e32 v75, v0
	v_mov_b32_e32 v76, v0
	v_mov_b32_e32 v77, v0
	v_mov_b32_e32 v78, v0
	v_mov_b32_e32 v79, v0
	v_mov_b32_e32 v88, v0
	v_mov_b32_e32 v89, v0
	v_mov_b32_e32 v90, v0
	v_mov_b32_e32 v91, v0
	v_mov_b32_e32 v92, v0
	v_mov_b32_e32 v93, v0
	v_mov_b32_e32 v94, v0
	v_mov_b32_e32 v95, v0
	v_mov_b32_e32 v104, v0
	v_mov_b32_e32 v105, v0
	v_mov_b32_e32 v106, v0
	v_mov_b32_e32 v107, v0
	v_mov_b32_e32 v108, v0
	v_mov_b32_e32 v109, v0
	v_mov_b32_e32 v110, v0
	v_mov_b32_e32 v111, v0
	v_mov_b32_e32 v120, v0
	v_mov_b32_e32 v121, v0
	v_mov_b32_e32 v122, v0
	v_mov_b32_e32 v123, v0
	v_mov_b32_e32 v124, v0
	v_mov_b32_e32 v125, v0
	v_mov_b32_e32 v126, v0
	v_mov_b32_e32 v127, v0
	.p2align 6

;     __device__ __forceinline__ bool next(int i, pg8::Unit& u) const { if (c < 128 || i >= 2) return false; const int idx = (c - 128) * 2 + i; u.pm = idx >> 2; u.pn = idx & 3; return true; }
; template <class Epi, class Sched, bool ALIGN_EPI = false, bool SP2 = false, bool F16 = false>
; __device__ __forceinline__ void gemm_phase(PG8_LAS unsigned char* lds, const Gemm g, const Sched& S, const Epi& E, const int wid_in) {
;     ...
;         const bool has_next = S.next(ui + 1, nxt);
;         const char* nA = has_next ? (const char*)g.A + (size_t)nxt.pm * tstep : cA; const char* nB = has_next ? (const char*)g.Bt + (size_t)nxt.pn * tstep : cB;
;         for (int t = 0; t < nt; t += 2) {
;             const bool last = (t == nt - 2);
;             const char* a1 = cA + (size_t)(t + 1) * kstep;
;             const char* a2 = last ? nA : cA + (size_t)(t + 2) * kstep; const char* b2 = last ? nB : cB + (size_t)(t + 2) * kstep;
;             const char* a3 = a2 + kstep; const char* b3 = b2 + kstep;
;     ...
; #pragma unroll
;         for (int a = 0; a < 2; ++a)
; #pragma unroll
;             for (int b = 0; b < 2; ++b)
; #pragma unroll
;                 for (int m = 0; m < 4; ++m)
; #pragma unroll
;                     for (int n = 0; n < 2; ++n) acc[a][b][m][n] = (f32x4){0.f, 0.f, 0.f, 0.f};
;         cur = nxt; cA = nA; cB = nB; ++ui;
.LBB0_2565:
	s_ashr_i32 s25, s24, 31
	s_lshl_b64 s[26:27], s[24:25], 19
	s_add_u32 s26, s41, s26
	s_addc_u32 s27, s46, s27
	s_and_b64 s[28:29], s[10:11], exec
	s_cselect_b32 s25, s27, s37
	s_cselect_b32 s35, s26, s36
	s_ashr_i32 s23, s22, 31
	s_lshl_b64 s[28:29], s[22:23], 19
	s_add_u32 s28, s47, s28
	s_addc_u32 s29, s48, s29
	s_and_b64 s[44:45], s[10:11], exec
	s_cselect_b32 s23, s29, s43
	s_cselect_b32 s59, s28, s42
	s_add_u32 s36, s36, 0x40080
	s_addc_u32 s37, s37, 0
	s_add_u32 s60, s42, 0x100
	v_mov_b32_e32 v8, 0
	s_addc_u32 s61, s43, 0
	s_mov_b32 s62, -2
	v_mov_b32_e32 v9, v8
	v_mov_b32_e32 v10, v8
	v_mov_b32_e32 v11, v8
	v_mov_b32_e32 v12, v8
	v_mov_b32_e32 v13, v8
	v_mov_b32_e32 v14, v8
	v_mov_b32_e32 v15, v8
	v_mov_b32_e32 v24, v8
	v_mov_b32_e32 v25, v8
	v_mov_b32_e32 v26, v8
	v_mov_b32_e32 v27, v8
	v_mov_b32_e32 v28, v8
	v_mov_b32_e32 v29, v8
	v_mov_b32_e32 v30, v8
	v_mov_b32_e32 v31, v8
	v_mov_b32_e32 v40, v8
	v_mov_b32_e32 v41, v8
	v_mov_b32_e32 v42, v8
	v_mov_b32_e32 v43, v8
	v_mov_b32_e32 v44, v8
	v_mov_b32_e32 v45, v8
	v_mov_b32_e32 v46, v8
	v_mov_b32_e32 v47, v8
	v_mov_b32_e32 v56, v8
	v_mov_b32_e32 v57, v8
	v_mov_b32_e32 v58, v8
	v_mov_b32_e32 v59, v8
	v_mov_b32_e32 v60, v8
	v_mov_b32_e32 v61, v8
	v_mov_b32_e32 v62, v8
	v_mov_b32_e32 v63, v8
	v_mov_b32_e32 v16, v8
	v_mov_b32_e32 v17, v8
	v_mov_b32_e32 v18, v8
	v_mov_b32_e32 v19, v8
	v_mov_b32_e32 v20, v8
	v_mov_b32_e32 v21, v8
	v_mov_b32_e32 v22, v8
	v_mov_b32_e32 v23, v8
	v_mov_b32_e32 v32, v8
	v_mov_b32_e32 v33, v8
	v_mov_b32_e32 v34, v8
	v_mov_b32_e32 v35, v8
	v_mov_b32_e32 v36, v8
	v_mov_b32_e32 v37, v8
	v_mov_b32_e32 v38, v8
	v_mov_b32_e32 v39, v8
	v_mov_b32_e32 v48, v8
	v_mov_b32_e32 v49, v8
	v_mov_b32_e32 v50, v8
	v_mov_b32_e32 v51, v8
	v_mov_b32_e32 v52, v8
	v_mov_b32_e32 v53, v8
	v_mov_b32_e32 v54, v8
	v_mov_b32_e32 v55, v8
	v_mov_b32_e32 v64, v8
	v_mov_b32_e32 v65, v8
	v_mov_b32_e32 v66, v8
	v_mov_b32_e32 v67, v8
	v_mov_b32_e32 v68, v8
	v_mov_b32_e32 v69, v8
	v_mov_b32_e32 v70, v8
	v_mov_b32_e32 v71, v8
	v_mov_b32_e32 v72, v8
	v_mov_b32_e32 v73, v8
	v_mov_b32_e32 v74, v8
	v_mov_b32_e32 v75, v8
	v_mov_b32_e32 v76, v8
	v_mov_b32_e32 v77, v8
	v_mov_b32_e32 v78, v8
	v_mov_b32_e32 v79, v8
	v_mov_b32_e32 v88, v8
	v_mov_b32_e32 v89, v8
	v_mov_b32_e32 v90, v8
	v_mov_b32_e32 v91, v8
	v_mov_b32_e32 v92, v8
	v_mov_b32_e32 v93, v8
	v_mov_b32_e32 v94, v8
	v_mov_b32_e32 v95, v8
	v_mov_b32_e32 v104, v8
	v_mov_b32_e32 v105, v8
	v_mov_b32_e32 v106, v8
	v_mov_b32_e32 v107, v8
	v_mov_b32_e32 v108, v8
	v_mov_b32_e32 v109, v8
	v_mov_b32_e32 v110, v8
	v_mov_b32_e32 v111, v8
	v_mov_b32_e32 v120, v8
	v_mov_b32_e32 v121, v8
	v_mov_b32_e32 v122, v8
	v_mov_b32_e32 v123, v8
	v_mov_b32_e32 v124, v8
	v_mov_b32_e32 v125, v8
	v_mov_b32_e32 v126, v8
	v_mov_b32_e32 v127, v8
	v_mov_b32_e32 v80, v8
	v_mov_b32_e32 v81, v8
	v_mov_b32_e32 v82, v8
	v_mov_b32_e32 v83, v8
	v_mov_b32_e32 v84, v8
	v_mov_b32_e32 v85, v8
	v_mov_b32_e32 v86, v8
	v_mov_b32_e32 v87, v8
	v_mov_b32_e32 v96, v8
	v_mov_b32_e32 v97, v8
	v_mov_b32_e32 v98, v8
	v_mov_b32_e32 v99, v8
	v_mov_b32_e32 v100, v8
	v_mov_b32_e32 v101, v8
	v_mov_b32_e32 v102, v8
	v_mov_b32_e32 v103, v8
	v_mov_b32_e32 v112, v8
	v_mov_b32_e32 v113, v8
	v_mov_b32_e32 v114, v8
	v_mov_b32_e32 v115, v8
	v_mov_b32_e32 v116, v8
	v_mov_b32_e32 v117, v8
	v_mov_b32_e32 v118, v8
	v_mov_b32_e32 v119, v8
	v_mov_b32_e32 v128, v8
	v_mov_b32_e32 v129, v8
	v_mov_b32_e32 v130, v8
	v_mov_b32_e32 v131, v8
	v_mov_b32_e32 v132, v8
	v_mov_b32_e32 v133, v8
	v_mov_b32_e32 v134, v8
	v_mov_b32_e32 v135, v8
	.p2align 6

; template <class Epi, class Sched, bool ALIGN_EPI = false, bool SP2 = false, bool F16 = false>
; __device__ __forceinline__ void gemm_phase(PG8_LAS unsigned char* lds, const Gemm g, const Sched& S, const Epi& E, const int wid_in) {
;     ...
;             const char* a1 = cA + (size_t)(t + 1) * kstep;
;             const char* a2 = last ? nA : cA + (size_t)(t + 2) * kstep; const char* b2 = last ? nB : cB + (size_t)(t + 2) * kstep;
;             const char* a3 = a2 + kstep; const char* b3 = b2 + kstep;
;     ...
; #pragma unroll
;         for (int a = 0; a < 2; ++a)
; #pragma unroll
;             for (int b = 0; b < 2; ++b)
; #pragma unroll
;                 for (int m = 0; m < 4; ++m)
; #pragma unroll
;                     for (int n = 0; n < 2; ++n) acc[a][b][m][n] = (f32x4){0.f, 0.f, 0.f, 0.f};
;         cur = nxt; cA = nA; cB = nB; ++ui;
.LBB0_2696:
	s_add_u32 s53, s30, 0x100
	v_mov_b32_e32 v0, 0
	s_addc_u32 s54, s31, 0
	s_mov_b32 s55, -2
	v_mov_b32_e32 v1, v0
	v_mov_b32_e32 v2, v0
	v_mov_b32_e32 v3, v0
	v_mov_b32_e32 v4, v0
	v_mov_b32_e32 v5, v0
	v_mov_b32_e32 v6, v0
	v_mov_b32_e32 v7, v0
	v_mov_b32_e32 v16, v0
	v_mov_b32_e32 v17, v0
	v_mov_b32_e32 v18, v0
	v_mov_b32_e32 v19, v0
	v_mov_b32_e32 v20, v0
	v_mov_b32_e32 v21, v0
	v_mov_b32_e32 v22, v0
	v_mov_b32_e32 v23, v0
	v_mov_b32_e32 v32, v0
	v_mov_b32_e32 v33, v0
	v_mov_b32_e32 v34, v0
	v_mov_b32_e32 v35, v0
	v_mov_b32_e32 v36, v0
	v_mov_b32_e32 v37, v0
	v_mov_b32_e32 v38, v0
	v_mov_b32_e32 v39, v0
	v_mov_b32_e32 v48, v0
	v_mov_b32_e32 v49, v0
	v_mov_b32_e32 v50, v0
	v_mov_b32_e32 v51, v0
	v_mov_b32_e32 v52, v0
	v_mov_b32_e32 v53, v0
	v_mov_b32_e32 v54, v0
	v_mov_b32_e32 v55, v0
	v_mov_b32_e32 v8, v0
	v_mov_b32_e32 v9, v0
	v_mov_b32_e32 v10, v0
	v_mov_b32_e32 v11, v0
	v_mov_b32_e32 v12, v0
	v_mov_b32_e32 v13, v0
	v_mov_b32_e32 v14, v0
	v_mov_b32_e32 v15, v0
	v_mov_b32_e32 v24, v0
	v_mov_b32_e32 v25, v0
	v_mov_b32_e32 v26, v0
	v_mov_b32_e32 v27, v0
	v_mov_b32_e32 v28, v0
	v_mov_b32_e32 v29, v0
	v_mov_b32_e32 v30, v0
	v_mov_b32_e32 v31, v0
	v_mov_b32_e32 v40, v0
	v_mov_b32_e32 v41, v0
	v_mov_b32_e32 v42, v0
	v_mov_b32_e32 v43, v0
	v_mov_b32_e32 v44, v0
	v_mov_b32_e32 v45, v0
	v_mov_b32_e32 v46, v0
	v_mov_b32_e32 v47, v0
	v_mov_b32_e32 v56, v0
	v_mov_b32_e32 v57, v0
	v_mov_b32_e32 v58, v0
	v_mov_b32_e32 v59, v0
	v_mov_b32_e32 v60, v0
	v_mov_b32_e32 v61, v0
	v_mov_b32_e32 v62, v0
	v_mov_b32_e32 v63, v0
	v_mov_b32_e32 v64, v0
	v_mov_b32_e32 v65, v0
	v_mov_b32_e32 v66, v0
	v_mov_b32_e32 v67, v0
	v_mov_b32_e32 v68, v0
	v_mov_b32_e32 v69, v0
	v_mov_b32_e32 v70, v0
	v_mov_b32_e32 v71, v0
	v_mov_b32_e32 v80, v0
	v_mov_b32_e32 v81, v0
	v_mov_b32_e32 v82, v0
	v_mov_b32_e32 v83, v0
	v_mov_b32_e32 v84, v0
	v_mov_b32_e32 v85, v0
	v_mov_b32_e32 v86, v0
	v_mov_b32_e32 v87, v0
	v_mov_b32_e32 v96, v0
	v_mov_b32_e32 v97, v0
	v_mov_b32_e32 v98, v0
	v_mov_b32_e32 v99, v0
	v_mov_b32_e32 v100, v0
	v_mov_b32_e32 v101, v0
	v_mov_b32_e32 v102, v0
	v_mov_b32_e32 v103, v0
	v_mov_b32_e32 v112, v0
	v_mov_b32_e32 v113, v0
	v_mov_b32_e32 v114, v0
	v_mov_b32_e32 v115, v0
	v_mov_b32_e32 v116, v0
	v_mov_b32_e32 v117, v0
	v_mov_b32_e32 v118, v0
	v_mov_b32_e32 v119, v0
	v_mov_b32_e32 v72, v0
	v_mov_b32_e32 v73, v0
	v_mov_b32_e32 v74, v0
	v_mov_b32_e32 v75, v0
	v_mov_b32_e32 v76, v0
	v_mov_b32_e32 v77, v0
	v_mov_b32_e32 v78, v0
	v_mov_b32_e32 v79, v0
	v_mov_b32_e32 v88, v0
	v_mov_b32_e32 v89, v0
	v_mov_b32_e32 v90, v0
	v_mov_b32_e32 v91, v0
	v_mov_b32_e32 v92, v0
	v_mov_b32_e32 v93, v0
	v_mov_b32_e32 v94, v0
	v_mov_b32_e32 v95, v0
	v_mov_b32_e32 v104, v0
	v_mov_b32_e32 v105, v0
	v_mov_b32_e32 v106, v0
	v_mov_b32_e32 v107, v0
	v_mov_b32_e32 v108, v0
	v_mov_b32_e32 v109, v0
	v_mov_b32_e32 v110, v0
	v_mov_b32_e32 v111, v0
	v_mov_b32_e32 v120, v0
	v_mov_b32_e32 v121, v0
	v_mov_b32_e32 v122, v0
	v_mov_b32_e32 v123, v0
	v_mov_b32_e32 v124, v0
	v_mov_b32_e32 v125, v0
	v_mov_b32_e32 v126, v0
	v_mov_b32_e32 v127, v0
	.p2align 6

;     __device__ __forceinline__ bool next(int i, pg8::Unit& u) const { if (c < 128 || i >= 2) return false; const int idx = (c - 128) * 2 + i; u.pm = idx >> 2; u.pn = idx & 3; return true; }
; template <class Epi, class Sched, bool ALIGN_EPI = false, bool SP2 = false, bool F16 = false>
; __device__ __forceinline__ void gemm_phase(PG8_LAS unsigned char* lds, const Gemm g, const Sched& S, const Epi& E, const int wid_in) {
;     ...
;         const bool has_next = S.next(ui + 1, nxt);
;         const char* nA = has_next ? (const char*)g.A + (size_t)nxt.pm * tstep : cA; const char* nB = has_next ? (const char*)g.Bt + (size_t)nxt.pn * tstep : cB;
;         for (int t = 0; t < nt; t += 2) {
;             const bool last = (t == nt - 2);
;             const char* a1 = cA + (size_t)(t + 1) * kstep;
;             const char* a2 = last ? nA : cA + (size_t)(t + 2) * kstep; const char* b2 = last ? nB : cB + (size_t)(t + 2) * kstep;
;             const char* a3 = a2 + kstep; const char* b3 = b2 + kstep;
;     ...
; #pragma unroll
;         for (int a = 0; a < 2; ++a)
; #pragma unroll
;             for (int b = 0; b < 2; ++b)
; #pragma unroll
;                 for (int m = 0; m < 4; ++m)
; #pragma unroll
;                     for (int n = 0; n < 2; ++n) acc[a][b][m][n] = (f32x4){0.f, 0.f, 0.f, 0.f};
;         cur = nxt; cA = nA; cB = nB; ++ui;
.LBB0_2792:
	s_ashr_i32 s31, s30, 31
	s_lshl_b64 s[14:15], s[30:31], 19
	s_add_u32 s34, s10, s14
	s_addc_u32 s35, s11, s15
	s_and_b64 s[14:15], s[8:9], exec
	s_cselect_b32 s14, s35, s43
	s_cselect_b32 s15, s34, s42
	s_ashr_i32 s29, s28, 31
	s_lshl_b64 s[36:37], s[28:29], 19
	s_add_u32 s36, s49, s36
	s_addc_u32 s37, s50, s37
	s_and_b64 s[46:47], s[8:9], exec
	s_cselect_b32 s29, s37, s45
	s_cselect_b32 s31, s36, s44
	s_add_u32 s42, s42, 0x40080
	s_addc_u32 s43, s43, 0
	s_add_u32 s41, s44, 0x100
	v_mov_b32_e32 v0, 0
	s_addc_u32 s58, s45, 0
	s_mov_b32 s59, -2
	v_mov_b32_e32 v1, v0
	v_mov_b32_e32 v2, v0
	v_mov_b32_e32 v3, v0
	v_mov_b32_e32 v4, v0
	v_mov_b32_e32 v5, v0
	v_mov_b32_e32 v6, v0
	v_mov_b32_e32 v7, v0
	v_mov_b32_e32 v16, v0
	v_mov_b32_e32 v17, v0
	v_mov_b32_e32 v18, v0
	v_mov_b32_e32 v19, v0
	v_mov_b32_e32 v20, v0
	v_mov_b32_e32 v21, v0
	v_mov_b32_e32 v22, v0
	v_mov_b32_e32 v23, v0
	v_mov_b32_e32 v32, v0
	v_mov_b32_e32 v33, v0
	v_mov_b32_e32 v34, v0
	v_mov_b32_e32 v35, v0
	v_mov_b32_e32 v36, v0
	v_mov_b32_e32 v37, v0
	v_mov_b32_e32 v38, v0
	v_mov_b32_e32 v39, v0
	v_mov_b32_e32 v48, v0
	v_mov_b32_e32 v49, v0
	v_mov_b32_e32 v50, v0
	v_mov_b32_e32 v51, v0
	v_mov_b32_e32 v52, v0
	v_mov_b32_e32 v53, v0
	v_mov_b32_e32 v54, v0
	v_mov_b32_e32 v55, v0
	v_mov_b32_e32 v8, v0
	v_mov_b32_e32 v9, v0
	v_mov_b32_e32 v10, v0
	v_mov_b32_e32 v11, v0
	v_mov_b32_e32 v12, v0
	v_mov_b32_e32 v13, v0
	v_mov_b32_e32 v14, v0
	v_mov_b32_e32 v15, v0
	v_mov_b32_e32 v24, v0
	v_mov_b32_e32 v25, v0
	v_mov_b32_e32 v26, v0
	v_mov_b32_e32 v27, v0
	v_mov_b32_e32 v28, v0
	v_mov_b32_e32 v29, v0
	v_mov_b32_e32 v30, v0
	v_mov_b32_e32 v31, v0
	v_mov_b32_e32 v40, v0
	v_mov_b32_e32 v41, v0
	v_mov_b32_e32 v42, v0
	v_mov_b32_e32 v43, v0
	v_mov_b32_e32 v44, v0
	v_mov_b32_e32 v45, v0
	v_mov_b32_e32 v46, v0
	v_mov_b32_e32 v47, v0
	v_mov_b32_e32 v56, v0
	v_mov_b32_e32 v57, v0
	v_mov_b32_e32 v58, v0
	v_mov_b32_e32 v59, v0
	v_mov_b32_e32 v60, v0
	v_mov_b32_e32 v61, v0
	v_mov_b32_e32 v62, v0
	v_mov_b32_e32 v63, v0
	v_mov_b32_e32 v64, v0
	v_mov_b32_e32 v65, v0
	v_mov_b32_e32 v66, v0
	v_mov_b32_e32 v67, v0
	v_mov_b32_e32 v68, v0
	v_mov_b32_e32 v69, v0
	v_mov_b32_e32 v70, v0
	v_mov_b32_e32 v71, v0
	v_mov_b32_e32 v80, v0
	v_mov_b32_e32 v81, v0
	v_mov_b32_e32 v82, v0
	v_mov_b32_e32 v83, v0
	v_mov_b32_e32 v84, v0
	v_mov_b32_e32 v85, v0
	v_mov_b32_e32 v86, v0
	v_mov_b32_e32 v87, v0
	v_mov_b32_e32 v96, v0
	v_mov_b32_e32 v97, v0
	v_mov_b32_e32 v98, v0
	v_mov_b32_e32 v99, v0
	v_mov_b32_e32 v100, v0
	v_mov_b32_e32 v101, v0
	v_mov_b32_e32 v102, v0
	v_mov_b32_e32 v103, v0
	v_mov_b32_e32 v120, v0
	v_mov_b32_e32 v121, v0
	v_mov_b32_e32 v122, v0
	v_mov_b32_e32 v123, v0
	v_mov_b32_e32 v124, v0
	v_mov_b32_e32 v125, v0
	v_mov_b32_e32 v126, v0
	v_mov_b32_e32 v127, v0
	v_mov_b32_e32 v72, v0
	v_mov_b32_e32 v73, v0
	v_mov_b32_e32 v74, v0
	v_mov_b32_e32 v75, v0
	v_mov_b32_e32 v76, v0
	v_mov_b32_e32 v77, v0
	v_mov_b32_e32 v78, v0
	v_mov_b32_e32 v79, v0
	v_mov_b32_e32 v88, v0
	v_mov_b32_e32 v89, v0
	v_mov_b32_e32 v90, v0
	v_mov_b32_e32 v91, v0
	v_mov_b32_e32 v92, v0
	v_mov_b32_e32 v93, v0
	v_mov_b32_e32 v94, v0
	v_mov_b32_e32 v95, v0
	v_mov_b32_e32 v104, v0
	v_mov_b32_e32 v105, v0
	v_mov_b32_e32 v106, v0
	v_mov_b32_e32 v107, v0
	v_mov_b32_e32 v108, v0
	v_mov_b32_e32 v109, v0
	v_mov_b32_e32 v110, v0
	v_mov_b32_e32 v111, v0
	v_mov_b32_e32 v136, v0
	v_mov_b32_e32 v137, v0
	v_mov_b32_e32 v138, v0
	v_mov_b32_e32 v139, v0
	v_mov_b32_e32 v140, v0
	v_mov_b32_e32 v141, v0
	v_mov_b32_e32 v142, v0
	v_mov_b32_e32 v143, v0
	.p2align 6
